# GEMM K-loops (in-proj, out-proj, ffn-in, ffn-out): loop-carried SALU rotated from behind the loop-back barrier to in front of it (back-edge rotation)
# baseline (speedup 1.0000x reference)
; #define PG8_STAGE(bufoff, gbase, voff) do { _Pragma("unroll") for (int _i = 0; _i < 2; ++_i) \
;         __builtin_amdgcn_global_load_lds((const unsigned*)((const char*)(gbase) + (voff)[_i]), (LAS unsigned*)(lds + (bufoff) + ldsw + _i * 8192), 16, 0, 0); } while (0)
; #define PG8_LDA(dst, b, h) do { _Pragma("unroll") for (int m = 0; m < 4; ++m) _Pragma("unroll") for (int k = 0; k < 2; ++k) dst[m][k] = *(const LAS bf16x8*)(lds + PG8_SA(b, h) + aoff + m * 2048 + k * 1024); } while (0)
; #define PG8_LDB(dst, b, h) do { _Pragma("unroll") for (int n = 0; n < 2; ++n) _Pragma("unroll") for (int k = 0; k < 2; ++k) dst[n][k] = *(const LAS bf16x8*)(lds + PG8_SB(b, h) + boff + n * 2048 + k * 1024); } while (0)
; #define PG8_WAIT_V(n) asm volatile("s_waitcnt vmcnt(" #n ")" ::: "memory")
; #define PG8_WAIT_L(n) asm volatile("s_waitcnt lgkmcnt(" #n ")" ::: "memory")
; template <class Epi, class Sched>
; __device__ __forceinline__ void gemm_phase(LAS unsigned char* lds, const Gemm g, const Sched& S, const Epi& E, const int tid) {
;     ...
;         const char* nA = has_next ? (const char*)g.A + (size_t)nxt.pm * tstep + (size_t)nxt.koff * 2 : cA; const char* nB = has_next ? (const char*)g.Bt + (size_t)nxt.pn * tstep + (size_t)nxt.koff * 2 : cB;
;         const int nt = cur.nt;
;         for (int t = 0; t < nt; t += 2) {
;             if constexpr (Epi::CHAIN) { if (t == 8 || t == 12) { E.mid(acc, cur, t == 8 ? 0 : 1, wr, wc, fr, fq); PG8_SCHED; } }
;             const bool last = (t == nt - 2);
;             const char* a1 = cA + (size_t)(t + 1) * kstep;
;             const char* a2 = last ? nA : cA + (size_t)(t + 2) * kstep; const char* b2 = last ? nB : cB + (size_t)(t + 2) * kstep;
;             const char* a3 = a2 + kstep; const char* b3 = b2 + kstep;
;             PG8_LDB(B0, 0, 0); PG8_LDB(B1, 0, 1); PG8_SCHED; PG8_LDA(At, 0, 0); PG8_STAGE(PG8_SA(1, 1), a1 + hstep, voffA);
;             PG8_WAIT_V(8); PG8_WAIT_L(0); PG8_BAR; PG8_MMA(0, 0, At, B0); PG8_MMA(0, 1, At, B1); PG8_BAR; PG8_SCHED;
;     ...
;         if (!(Epi::CHAIN && nxt.seg != 0))
; #pragma unroll
;         for (int a = 0; a < 2; ++a)
; #pragma unroll
;             for (int b = 0; b < 2; ++b)
; #pragma unroll
;                 for (int m = 0; m < 4; ++m)
; #pragma unroll
;                     for (int n = 0; n < 2; ++n) acc[a][b][m][n] = (f32x4){0.f, 0.f, 0.f, 0.f};
;         cur = nxt; cA = nA; cB = nB; ++ui;
.LBB0_29:
	s_ashr_i32 s23, s22, 31
	s_lshl_b64 s[26:27], s[22:23], 19
	s_add_u32 s48, s21, s26
	s_addc_u32 s49, s36, s27
	s_and_b64 s[26:27], s[6:7], exec
	s_cselect_b32 s23, s49, s55
	s_cselect_b32 s70, s48, s54
	s_ashr_i32 s19, s18, 31
	s_lshl_b64 s[26:27], s[18:19], 19
	s_add_u32 s50, s42, s26
	s_addc_u32 s51, s43, s27
	s_and_b64 s[26:27], s[6:7], exec
	s_cselect_b32 s19, s51, s57
	s_cselect_b32 s71, s50, s56
	s_add_u32 s54, s54, 0x40080
	s_addc_u32 s55, s55, 0
	s_add_u32 s76, s56, 0x100
	v_mov_b32_e32 v2, 0
	s_addc_u32 s79, s57, 0
	s_mov_b32 s72, -2
	v_mov_b32_e32 v3, v2
	v_mov_b32_e32 v4, v2
	v_mov_b32_e32 v5, v2
	v_mov_b32_e32 v6, v2
	v_mov_b32_e32 v7, v2
	v_mov_b32_e32 v8, v2
	v_mov_b32_e32 v9, v2
	v_mov_b32_e32 v14, v2
	v_mov_b32_e32 v15, v2
	v_mov_b32_e32 v16, v2
	v_mov_b32_e32 v17, v2
	v_mov_b32_e32 v22, v2
	v_mov_b32_e32 v23, v2
	v_mov_b32_e32 v24, v2
	v_mov_b32_e32 v25, v2
	v_mov_b32_e32 v30, v2
	v_mov_b32_e32 v31, v2
	v_mov_b32_e32 v32, v2
	v_mov_b32_e32 v33, v2
	v_mov_b32_e32 v38, v2
	v_mov_b32_e32 v39, v2
	v_mov_b32_e32 v40, v2
	v_mov_b32_e32 v41, v2
	v_mov_b32_e32 v46, v2
	v_mov_b32_e32 v47, v2
	v_mov_b32_e32 v48, v2
	v_mov_b32_e32 v49, v2
	v_mov_b32_e32 v54, v2
	v_mov_b32_e32 v55, v2
	v_mov_b32_e32 v56, v2
	v_mov_b32_e32 v57, v2
	v_mov_b32_e32 v10, v2
	v_mov_b32_e32 v11, v2
	v_mov_b32_e32 v12, v2
	v_mov_b32_e32 v13, v2
	v_mov_b32_e32 v18, v2
	v_mov_b32_e32 v19, v2
	v_mov_b32_e32 v20, v2
	v_mov_b32_e32 v21, v2
	v_mov_b32_e32 v26, v2
	v_mov_b32_e32 v27, v2
	v_mov_b32_e32 v28, v2
	v_mov_b32_e32 v29, v2
	v_mov_b32_e32 v34, v2
	v_mov_b32_e32 v35, v2
	v_mov_b32_e32 v36, v2
	v_mov_b32_e32 v37, v2
	v_mov_b32_e32 v42, v2
	v_mov_b32_e32 v43, v2
	v_mov_b32_e32 v44, v2
	v_mov_b32_e32 v45, v2
	v_mov_b32_e32 v50, v2
	v_mov_b32_e32 v51, v2
	v_mov_b32_e32 v52, v2
	v_mov_b32_e32 v53, v2
	v_mov_b32_e32 v58, v2
	v_mov_b32_e32 v59, v2
	v_mov_b32_e32 v60, v2
	v_mov_b32_e32 v61, v2
	v_mov_b32_e32 v62, v2
	v_mov_b32_e32 v63, v2
	v_mov_b32_e32 v64, v2
	v_mov_b32_e32 v65, v2
	v_mov_b32_e32 v66, v2
	v_mov_b32_e32 v67, v2
	v_mov_b32_e32 v68, v2
	v_mov_b32_e32 v69, v2
	v_mov_b32_e32 v70, v2
	v_mov_b32_e32 v71, v2
	v_mov_b32_e32 v72, v2
	v_mov_b32_e32 v73, v2
	v_mov_b32_e32 v78, v2
	v_mov_b32_e32 v79, v2
	v_mov_b32_e32 v80, v2
	v_mov_b32_e32 v81, v2
	s_waitcnt vmcnt(0)
	v_mov_b32_e32 v86, v2
	v_mov_b32_e32 v87, v2
	v_mov_b32_e32 v88, v2
	v_mov_b32_e32 v89, v2
	v_mov_b32_e32 v94, v2
	v_mov_b32_e32 v95, v2
	v_mov_b32_e32 v96, v2
	v_mov_b32_e32 v97, v2
	v_mov_b32_e32 v102, v2
	v_mov_b32_e32 v103, v2
	v_mov_b32_e32 v104, v2
	v_mov_b32_e32 v105, v2
	v_mov_b32_e32 v110, v2
	v_mov_b32_e32 v111, v2
	v_mov_b32_e32 v112, v2
	v_mov_b32_e32 v113, v2
	v_mov_b32_e32 v118, v2
	v_mov_b32_e32 v119, v2
	v_mov_b32_e32 v120, v2
	v_mov_b32_e32 v121, v2
	v_mov_b32_e32 v74, v2
	v_mov_b32_e32 v75, v2
	v_mov_b32_e32 v76, v2
	v_mov_b32_e32 v77, v2
	v_mov_b32_e32 v82, v2
	v_mov_b32_e32 v83, v2
	v_mov_b32_e32 v84, v2
	v_mov_b32_e32 v85, v2
	v_mov_b32_e32 v90, v2
	v_mov_b32_e32 v91, v2
	v_mov_b32_e32 v92, v2
	v_mov_b32_e32 v93, v2
	v_mov_b32_e32 v98, v2
	v_mov_b32_e32 v99, v2
	v_mov_b32_e32 v100, v2
	v_mov_b32_e32 v101, v2
	v_mov_b32_e32 v106, v2
	v_mov_b32_e32 v107, v2
	v_mov_b32_e32 v108, v2
	v_mov_b32_e32 v109, v2
	v_mov_b32_e32 v114, v2
	v_mov_b32_e32 v115, v2
	v_mov_b32_e32 v116, v2
	v_mov_b32_e32 v117, v2
	v_mov_b32_e32 v122, v2
	v_mov_b32_e32 v123, v2
	v_mov_b32_e32 v124, v2
	v_mov_b32_e32 v125, v2
	v_mov_b32_e32 v126, v2
	v_mov_b32_e32 v127, v2
	v_mov_b32_e32 v128, v2
	v_mov_b32_e32 v129, v2
	s_add_u32 s26, s54, 0xfffc0080
	s_addc_u32 s27, s55, -1
	s_add_i32 s30, 0, 0x10000
	s_cmp_eq_u32 s72, 12
	s_cselect_b32 s59, s23, s27
	s_cselect_b32 s58, s70, s26
	s_cselect_b32 s57, s19, s79
	s_cselect_b32 s56, s71, s76
	s_add_i32 s81, 0, 0x14000
.LBB0_30:
	v_add_u32_e32 v142, s30, v156
	ds_read_b128 v[162:165], v142
	ds_read_b128 v[166:169], v142 offset:1024
	ds_read_b128 v[170:173], v142 offset:2048
	ds_read_b128 v[174:177], v142 offset:3072
	v_add_u32_e32 v142, s81, v156
	ds_read_b128 v[178:181], v142
	ds_read_b128 v[198:201], v142 offset:1024
	ds_read_b128 v[202:205], v142 offset:2048
	ds_read_b128 v[206:209], v142 offset:3072
	v_lshl_add_u64 v[142:143], s[54:55], 0, v[138:139]
	s_add_i32 m0, s44, 0xc000
	ds_read_b128 v[210:213], v160
	ds_read_b128 v[214:217], v160 offset:1024
	ds_read_b128 v[218:221], v160 offset:2048
	ds_read_b128 v[222:225], v160 offset:3072
	ds_read_b128 v[226:229], v160 offset:4096
	ds_read_b128 v[230:233], v160 offset:5120
	ds_read_b128 v[234:237], v160 offset:6144
	ds_read_b128 v[238:241], v160 offset:7168
	global_load_lds_dwordx4 v[142:143], off
	v_lshl_add_u64 v[142:143], s[54:55], 0, v[140:141]
	s_add_i32 m0, s44, 0xe000
	s_nop 0
	global_load_lds_dwordx4 v[142:143], off
	s_waitcnt vmcnt(8)
	s_waitcnt lgkmcnt(0)
	s_barrier
; #define PG8_STAGE(bufoff, gbase, voff) do { _Pragma("unroll") for (int _i = 0; _i < 2; ++_i) \
;         __builtin_amdgcn_global_load_lds((const unsigned*)((const char*)(gbase) + (voff)[_i]), (LAS unsigned*)(lds + (bufoff) + ldsw + _i * 8192), 16, 0, 0); } while (0)
; #define PG8_LDA(dst, b, h) do { _Pragma("unroll") for (int m = 0; m < 4; ++m) _Pragma("unroll") for (int k = 0; k < 2; ++k) dst[m][k] = *(const LAS bf16x8*)(lds + PG8_SA(b, h) + aoff + m * 2048 + k * 1024); } while (0)
; #define PG8_MMA(ai, bj, At, Bt) do { __builtin_amdgcn_s_setprio(1); _Pragma("unroll") for (int m = 0; m < 4; ++m) _Pragma("unroll") for (int n = 0; n < 2; ++n) _Pragma("unroll") for (int k = 0; k < 2; ++k) \
;         acc[ai][bj][m][n] = __builtin_amdgcn_mfma_f32_16x16x32_bf16(Bt[n][k], At[m][k], acc[ai][bj][m][n], 0, 0, 0); __builtin_amdgcn_s_setprio(0); } while (0)
; #define PG8_WAIT_V(n) asm volatile("s_waitcnt vmcnt(" #n ")" ::: "memory")
; #define PG8_WAIT_L(n) asm volatile("s_waitcnt lgkmcnt(" #n ")" ::: "memory")
; #define PG8_BAR __builtin_amdgcn_s_barrier()
; #define PG8_SCHED __builtin_amdgcn_sched_barrier(0)
; template <class Epi, class Sched>
; __device__ __forceinline__ void gemm_phase(LAS unsigned char* lds, const Gemm g, const Sched& S, const Epi& E, const int tid) {
;     ...
;             PG8_WAIT_V(8); PG8_WAIT_L(0); PG8_BAR; PG8_MMA(0, 0, At, B0); PG8_MMA(0, 1, At, B1); PG8_BAR; PG8_SCHED;
;             PG8_LDA(At, 0, 1); PG8_STAGE(PG8_SB(0, 0), b2, voffB); PG8_STAGE(PG8_SB(0, 1), b2 + hstep, voffB); PG8_STAGE(PG8_SA(0, 0), a2, voffA);
;             PG8_WAIT_V(8); PG8_WAIT_L(0); PG8_BAR; PG8_MMA(1, 0, At, B0); PG8_MMA(1, 1, At, B1); PG8_BAR; PG8_SCHED;
	s_setprio 1
	s_waitcnt lgkmcnt(0)
	v_mfma_f32_16x16x32_bf16 v[126:129], v[162:165], v[210:213], v[126:129]
	v_mfma_f32_16x16x32_bf16 v[122:125], v[170:173], v[210:213], v[122:125]
	v_mfma_f32_16x16x32_bf16 v[114:117], v[162:165], v[218:221], v[114:117]
	v_mfma_f32_16x16x32_bf16 v[106:109], v[170:173], v[218:221], v[106:109]
	v_mfma_f32_16x16x32_bf16 v[98:101], v[162:165], v[226:229], v[98:101]
	v_mfma_f32_16x16x32_bf16 v[90:93], v[170:173], v[226:229], v[90:93]
	v_mfma_f32_16x16x32_bf16 v[82:85], v[162:165], v[234:237], v[82:85]
	v_mfma_f32_16x16x32_bf16 v[74:77], v[170:173], v[234:237], v[74:77]
	v_mfma_f32_16x16x32_bf16 v[126:129], v[166:169], v[214:217], v[126:129]
	v_mfma_f32_16x16x32_bf16 v[122:125], v[174:177], v[214:217], v[122:125]
	v_mfma_f32_16x16x32_bf16 v[114:117], v[166:169], v[222:225], v[114:117]
	v_mfma_f32_16x16x32_bf16 v[106:109], v[174:177], v[222:225], v[106:109]
	v_mfma_f32_16x16x32_bf16 v[98:101], v[166:169], v[230:233], v[98:101]
	v_mfma_f32_16x16x32_bf16 v[90:93], v[174:177], v[230:233], v[90:93]
	v_mfma_f32_16x16x32_bf16 v[82:85], v[166:169], v[238:241], v[82:85]
	v_mfma_f32_16x16x32_bf16 v[74:77], v[174:177], v[238:241], v[74:77]
	s_setprio 0
	s_setprio 1
	v_mfma_f32_16x16x32_bf16 v[118:121], v[178:181], v[210:213], v[118:121]
	v_mfma_f32_16x16x32_bf16 v[110:113], v[202:205], v[210:213], v[110:113]
	v_mfma_f32_16x16x32_bf16 v[102:105], v[178:181], v[218:221], v[102:105]
	v_mfma_f32_16x16x32_bf16 v[94:97], v[202:205], v[218:221], v[94:97]
	v_mfma_f32_16x16x32_bf16 v[86:89], v[178:181], v[226:229], v[86:89]
	v_mfma_f32_16x16x32_bf16 v[78:81], v[202:205], v[226:229], v[78:81]
	v_mfma_f32_16x16x32_bf16 v[70:73], v[178:181], v[234:237], v[70:73]
	v_mfma_f32_16x16x32_bf16 v[66:69], v[202:205], v[234:237], v[66:69]
	v_mfma_f32_16x16x32_bf16 v[118:121], v[198:201], v[214:217], v[118:121]
	v_mfma_f32_16x16x32_bf16 v[110:113], v[206:209], v[214:217], v[110:113]
	v_mfma_f32_16x16x32_bf16 v[102:105], v[198:201], v[222:225], v[102:105]
	v_mfma_f32_16x16x32_bf16 v[94:97], v[206:209], v[222:225], v[94:97]
	v_mfma_f32_16x16x32_bf16 v[86:89], v[198:201], v[230:233], v[86:89]
	v_mfma_f32_16x16x32_bf16 v[78:81], v[206:209], v[230:233], v[78:81]
	v_mfma_f32_16x16x32_bf16 v[70:73], v[198:201], v[238:241], v[70:73]
	v_mfma_f32_16x16x32_bf16 v[66:69], v[206:209], v[238:241], v[66:69]
	s_setprio 0
	s_barrier
	s_add_i32 s26, s30, s28
	v_lshl_add_u64 v[142:143], s[56:57], 0, v[0:1]
	s_mov_b32 m0, s26
	ds_read_b128 v[210:213], v160 offset:16384
	ds_read_b128 v[214:217], v160 offset:17408
	ds_read_b128 v[218:221], v160 offset:18432
	ds_read_b128 v[222:225], v160 offset:19456
	ds_read_b128 v[226:229], v160 offset:20480
	ds_read_b128 v[230:233], v160 offset:21504
	ds_read_b128 v[234:237], v160 offset:22528
	ds_read_b128 v[238:241], v160 offset:23552
	global_load_lds_dwordx4 v[142:143], off
	s_add_i32 m0, s26, 0x2000
	s_add_u32 s26, s56, 0x40000
	v_lshl_add_u64 v[182:183], s[56:57], 0, v[136:137]
	s_addc_u32 s27, s57, 0
	s_add_i32 s30, s81, s28
	global_load_lds_dwordx4 v[182:183], off
	v_lshl_add_u64 v[192:193], s[26:27], 0, v[0:1]
	s_mov_b32 m0, s30
	v_lshl_add_u64 v[242:243], s[58:59], 0, v[134:135]
	global_load_lds_dwordx4 v[192:193], off
	v_lshl_add_u64 v[192:193], s[26:27], 0, v[136:137]
	s_add_i32 m0, s30, 0x2000
	s_nop 0
	global_load_lds_dwordx4 v[192:193], off
	v_lshl_add_u64 v[192:193], s[58:59], 0, v[132:133]
	s_mov_b32 m0, s44
	s_nop 0
	global_load_lds_dwordx4 v[192:193], off
	s_mov_b32 m0, s45
	s_nop 0
	global_load_lds_dwordx4 v[242:243], off
	s_waitcnt vmcnt(8)
	s_waitcnt lgkmcnt(0)
	s_barrier
	s_setprio 1
	s_waitcnt lgkmcnt(0)
	v_mfma_f32_16x16x32_bf16 v[62:65], v[162:165], v[210:213], v[62:65]
	v_mfma_f32_16x16x32_bf16 v[58:61], v[170:173], v[210:213], v[58:61]
	v_mfma_f32_16x16x32_bf16 v[50:53], v[162:165], v[218:221], v[50:53]
	v_mfma_f32_16x16x32_bf16 v[42:45], v[170:173], v[218:221], v[42:45]
	v_mfma_f32_16x16x32_bf16 v[34:37], v[162:165], v[226:229], v[34:37]
	v_mfma_f32_16x16x32_bf16 v[26:29], v[170:173], v[226:229], v[26:29]
	v_mfma_f32_16x16x32_bf16 v[18:21], v[162:165], v[234:237], v[18:21]
	v_mfma_f32_16x16x32_bf16 v[10:13], v[170:173], v[234:237], v[10:13]
	v_mfma_f32_16x16x32_bf16 v[62:65], v[166:169], v[214:217], v[62:65]
	v_mfma_f32_16x16x32_bf16 v[58:61], v[174:177], v[214:217], v[58:61]
	v_mfma_f32_16x16x32_bf16 v[50:53], v[166:169], v[222:225], v[50:53]
	v_mfma_f32_16x16x32_bf16 v[42:45], v[174:177], v[222:225], v[42:45]
	v_mfma_f32_16x16x32_bf16 v[34:37], v[166:169], v[230:233], v[34:37]
	v_mfma_f32_16x16x32_bf16 v[26:29], v[174:177], v[230:233], v[26:29]
	v_mfma_f32_16x16x32_bf16 v[18:21], v[166:169], v[238:241], v[18:21]
	v_mfma_f32_16x16x32_bf16 v[10:13], v[174:177], v[238:241], v[10:13]
	s_setprio 0
	s_setprio 1
	v_mfma_f32_16x16x32_bf16 v[54:57], v[178:181], v[210:213], v[54:57]
	v_mfma_f32_16x16x32_bf16 v[46:49], v[202:205], v[210:213], v[46:49]
	v_mfma_f32_16x16x32_bf16 v[38:41], v[178:181], v[218:221], v[38:41]
	v_mfma_f32_16x16x32_bf16 v[30:33], v[202:205], v[218:221], v[30:33]
	v_mfma_f32_16x16x32_bf16 v[22:25], v[178:181], v[226:229], v[22:25]
	v_mfma_f32_16x16x32_bf16 v[14:17], v[202:205], v[226:229], v[14:17]
	v_mfma_f32_16x16x32_bf16 v[6:9], v[178:181], v[234:237], v[6:9]
	v_mfma_f32_16x16x32_bf16 v[2:5], v[202:205], v[234:237], v[2:5]
	v_mfma_f32_16x16x32_bf16 v[54:57], v[198:201], v[214:217], v[54:57]
	v_mfma_f32_16x16x32_bf16 v[46:49], v[206:209], v[214:217], v[46:49]
	v_mfma_f32_16x16x32_bf16 v[38:41], v[198:201], v[222:225], v[38:41]
	v_mfma_f32_16x16x32_bf16 v[30:33], v[206:209], v[222:225], v[30:33]
	v_mfma_f32_16x16x32_bf16 v[22:25], v[198:201], v[230:233], v[22:25]
	v_mfma_f32_16x16x32_bf16 v[14:17], v[206:209], v[230:233], v[14:17]
	v_mfma_f32_16x16x32_bf16 v[6:9], v[198:201], v[238:241], v[6:9]
	v_mfma_f32_16x16x32_bf16 v[2:5], v[206:209], v[238:241], v[2:5]
	s_setprio 0
	s_barrier
; #define PG8_STAGE(bufoff, gbase, voff) do { _Pragma("unroll") for (int _i = 0; _i < 2; ++_i) \
;         __builtin_amdgcn_global_load_lds((const unsigned*)((const char*)(gbase) + (voff)[_i]), (LAS unsigned*)(lds + (bufoff) + ldsw + _i * 8192), 16, 0, 0); } while (0)
; #define PG8_LDA(dst, b, h) do { _Pragma("unroll") for (int m = 0; m < 4; ++m) _Pragma("unroll") for (int k = 0; k < 2; ++k) dst[m][k] = *(const LAS bf16x8*)(lds + PG8_SA(b, h) + aoff + m * 2048 + k * 1024); } while (0)
; #define PG8_LDB(dst, b, h) do { _Pragma("unroll") for (int n = 0; n < 2; ++n) _Pragma("unroll") for (int k = 0; k < 2; ++k) dst[n][k] = *(const LAS bf16x8*)(lds + PG8_SB(b, h) + boff + n * 2048 + k * 1024); } while (0)
; #define PG8_MMA(ai, bj, At, Bt) do { __builtin_amdgcn_s_setprio(1); _Pragma("unroll") for (int m = 0; m < 4; ++m) _Pragma("unroll") for (int n = 0; n < 2; ++n) _Pragma("unroll") for (int k = 0; k < 2; ++k) \
;         acc[ai][bj][m][n] = __builtin_amdgcn_mfma_f32_16x16x32_bf16(Bt[n][k], At[m][k], acc[ai][bj][m][n], 0, 0, 0); __builtin_amdgcn_s_setprio(0); } while (0)
; #define PG8_WAIT_V(n) asm volatile("s_waitcnt vmcnt(" #n ")" ::: "memory")
; #define PG8_WAIT_L(n) asm volatile("s_waitcnt lgkmcnt(" #n ")" ::: "memory")
; #define PG8_BAR __builtin_amdgcn_s_barrier()
; #define PG8_SCHED __builtin_amdgcn_sched_barrier(0)
; template <class Epi, class Sched>
; __device__ __forceinline__ void gemm_phase(LAS unsigned char* lds, const Gemm g, const Sched& S, const Epi& E, const int tid) {
;     ...
;             PG8_LDB(B0, 1, 0); PG8_LDB(B1, 1, 1); PG8_SCHED; PG8_LDA(At, 1, 0); PG8_STAGE(PG8_SA(0, 1), a2 + hstep, voffA);
;             PG8_WAIT_V(8); PG8_WAIT_L(0); PG8_BAR; PG8_MMA(0, 0, At, B0); PG8_MMA(0, 1, At, B1); PG8_BAR; PG8_SCHED;
	s_add_i32 s30, 0, 0x18000
	v_add_u32_e32 v161, s30, v156
	s_add_i32 s81, 0, 0x1c000
	ds_read_b128 v[162:165], v161
	ds_read_b128 v[166:169], v161 offset:1024
	ds_read_b128 v[170:173], v161 offset:2048
	ds_read_b128 v[174:177], v161 offset:3072
	v_add_u32_e32 v161, s81, v156
	ds_read_b128 v[178:181], v161
	ds_read_b128 v[198:201], v161 offset:1024
	ds_read_b128 v[202:205], v161 offset:2048
	ds_read_b128 v[206:209], v161 offset:3072
	s_add_u32 s26, s58, 0x40000
	s_addc_u32 s27, s59, 0
	s_mov_b32 m0, s53
	v_lshl_add_u64 v[244:245], s[26:27], 0, v[132:133]
	ds_read_b128 v[210:213], v160 offset:32768
	ds_read_b128 v[214:217], v160 offset:33792
	ds_read_b128 v[218:221], v160 offset:34816
	ds_read_b128 v[222:225], v160 offset:35840
	ds_read_b128 v[226:229], v160 offset:36864
	ds_read_b128 v[230:233], v160 offset:37888
	ds_read_b128 v[234:237], v160 offset:38912
	ds_read_b128 v[238:241], v160 offset:39936
	global_load_lds_dwordx4 v[244:245], off
	v_lshl_add_u64 v[244:245], s[26:27], 0, v[134:135]
	s_mov_b32 m0, s60
	s_nop 0
	global_load_lds_dwordx4 v[244:245], off
	s_waitcnt vmcnt(8)
	s_waitcnt lgkmcnt(0)
	s_barrier
	s_setprio 1
	s_waitcnt lgkmcnt(0)
	v_mfma_f32_16x16x32_bf16 v[126:129], v[162:165], v[210:213], v[126:129]
	v_mfma_f32_16x16x32_bf16 v[122:125], v[170:173], v[210:213], v[122:125]
	v_mfma_f32_16x16x32_bf16 v[114:117], v[162:165], v[218:221], v[114:117]
	v_mfma_f32_16x16x32_bf16 v[106:109], v[170:173], v[218:221], v[106:109]
	v_mfma_f32_16x16x32_bf16 v[98:101], v[162:165], v[226:229], v[98:101]
	v_mfma_f32_16x16x32_bf16 v[90:93], v[170:173], v[226:229], v[90:93]
	v_mfma_f32_16x16x32_bf16 v[82:85], v[162:165], v[234:237], v[82:85]
	v_mfma_f32_16x16x32_bf16 v[74:77], v[170:173], v[234:237], v[74:77]
	v_mfma_f32_16x16x32_bf16 v[126:129], v[166:169], v[214:217], v[126:129]
	v_mfma_f32_16x16x32_bf16 v[122:125], v[174:177], v[214:217], v[122:125]
	v_mfma_f32_16x16x32_bf16 v[114:117], v[166:169], v[222:225], v[114:117]
	v_mfma_f32_16x16x32_bf16 v[106:109], v[174:177], v[222:225], v[106:109]
	v_mfma_f32_16x16x32_bf16 v[98:101], v[166:169], v[230:233], v[98:101]
	v_mfma_f32_16x16x32_bf16 v[90:93], v[174:177], v[230:233], v[90:93]
	v_mfma_f32_16x16x32_bf16 v[82:85], v[166:169], v[238:241], v[82:85]
	v_mfma_f32_16x16x32_bf16 v[74:77], v[174:177], v[238:241], v[74:77]
	s_setprio 0
	s_setprio 1
	v_mfma_f32_16x16x32_bf16 v[118:121], v[178:181], v[210:213], v[118:121]
	v_mfma_f32_16x16x32_bf16 v[110:113], v[202:205], v[210:213], v[110:113]
	v_mfma_f32_16x16x32_bf16 v[102:105], v[178:181], v[218:221], v[102:105]
	v_mfma_f32_16x16x32_bf16 v[94:97], v[202:205], v[218:221], v[94:97]
	v_mfma_f32_16x16x32_bf16 v[86:89], v[178:181], v[226:229], v[86:89]
	v_mfma_f32_16x16x32_bf16 v[78:81], v[202:205], v[226:229], v[78:81]
	v_mfma_f32_16x16x32_bf16 v[70:73], v[178:181], v[234:237], v[70:73]
	v_mfma_f32_16x16x32_bf16 v[66:69], v[202:205], v[234:237], v[66:69]
	v_mfma_f32_16x16x32_bf16 v[118:121], v[198:201], v[214:217], v[118:121]
	v_mfma_f32_16x16x32_bf16 v[110:113], v[206:209], v[214:217], v[110:113]
	v_mfma_f32_16x16x32_bf16 v[102:105], v[198:201], v[222:225], v[102:105]
	v_mfma_f32_16x16x32_bf16 v[94:97], v[206:209], v[222:225], v[94:97]
	v_mfma_f32_16x16x32_bf16 v[86:89], v[198:201], v[230:233], v[86:89]
	v_mfma_f32_16x16x32_bf16 v[78:81], v[206:209], v[230:233], v[78:81]
	v_mfma_f32_16x16x32_bf16 v[70:73], v[198:201], v[238:241], v[70:73]
	v_mfma_f32_16x16x32_bf16 v[66:69], v[206:209], v[238:241], v[66:69]
	s_setprio 0
	s_barrier
; #define PG8_STAGE(bufoff, gbase, voff) do { _Pragma("unroll") for (int _i = 0; _i < 2; ++_i) \
;         __builtin_amdgcn_global_load_lds((const unsigned*)((const char*)(gbase) + (voff)[_i]), (LAS unsigned*)(lds + (bufoff) + ldsw + _i * 8192), 16, 0, 0); } while (0)
; #define PG8_LDA(dst, b, h) do { _Pragma("unroll") for (int m = 0; m < 4; ++m) _Pragma("unroll") for (int k = 0; k < 2; ++k) dst[m][k] = *(const LAS bf16x8*)(lds + PG8_SA(b, h) + aoff + m * 2048 + k * 1024); } while (0)
; #define PG8_MMA(ai, bj, At, Bt) do { __builtin_amdgcn_s_setprio(1); _Pragma("unroll") for (int m = 0; m < 4; ++m) _Pragma("unroll") for (int n = 0; n < 2; ++n) _Pragma("unroll") for (int k = 0; k < 2; ++k) \
;         acc[ai][bj][m][n] = __builtin_amdgcn_mfma_f32_16x16x32_bf16(Bt[n][k], At[m][k], acc[ai][bj][m][n], 0, 0, 0); __builtin_amdgcn_s_setprio(0); } while (0)
; #define PG8_WAIT_V(n) asm volatile("s_waitcnt vmcnt(" #n ")" ::: "memory")
; #define PG8_WAIT_L(n) asm volatile("s_waitcnt lgkmcnt(" #n ")" ::: "memory")
; #define PG8_BAR __builtin_amdgcn_s_barrier()
; #define PG8_SCHED __builtin_amdgcn_sched_barrier(0)
; template <class Epi, class Sched>
; __device__ __forceinline__ void gemm_phase(LAS unsigned char* lds, const Gemm g, const Sched& S, const Epi& E, const int tid) {
;     ...
;         for (int t = 0; t < nt; t += 2) {
;             if constexpr (Epi::CHAIN) { if (t == 8 || t == 12) { E.mid(acc, cur, t == 8 ? 0 : 1, wr, wc, fr, fq); PG8_SCHED; } }
;             const bool last = (t == nt - 2);
;             const char* a1 = cA + (size_t)(t + 1) * kstep;
;             const char* a2 = last ? nA : cA + (size_t)(t + 2) * kstep; const char* b2 = last ? nB : cB + (size_t)(t + 2) * kstep;
;             const char* a3 = a2 + kstep; const char* b3 = b2 + kstep;
;     ...
;             PG8_LDA(At, 1, 1); PG8_STAGE(PG8_SB(1, 0), b3, voffB); PG8_STAGE(PG8_SB(1, 1), b3 + hstep, voffB); PG8_STAGE(PG8_SA(1, 0), a3, voffA);
;             PG8_WAIT_V(8); PG8_WAIT_L(0); PG8_BAR; PG8_MMA(1, 0, At, B0); PG8_MMA(1, 1, At, B1); PG8_BAR; PG8_SCHED;
;         }
	s_add_i32 s26, s30, s28
	v_lshl_add_u64 v[142:143], v[142:143], 0, s[34:35]
	s_mov_b32 m0, s26
	ds_read_b128 v[210:213], v160 offset:49152
	ds_read_b128 v[214:217], v160 offset:50176
	ds_read_b128 v[218:221], v160 offset:51200
	ds_read_b128 v[222:225], v160 offset:52224
	ds_read_b128 v[226:229], v160 offset:53248
	ds_read_b128 v[230:233], v160 offset:54272
	ds_read_b128 v[234:237], v160 offset:55296
	ds_read_b128 v[238:241], v160 offset:56320
	global_load_lds_dwordx4 v[142:143], off
	s_add_i32 m0, s26, 0x2000
	s_add_u32 s26, s56, 0x40080
	v_lshl_add_u64 v[142:143], v[182:183], 0, s[34:35]
	s_addc_u32 s27, s57, 0
	s_add_i32 s30, s81, s28
	global_load_lds_dwordx4 v[142:143], off
	v_lshl_add_u64 v[142:143], s[26:27], 0, v[0:1]
	s_mov_b32 m0, s30
	s_nop 0
	global_load_lds_dwordx4 v[142:143], off
	v_lshl_add_u64 v[142:143], s[26:27], 0, v[136:137]
	s_add_i32 m0, s30, 0x2000
	s_nop 0
	global_load_lds_dwordx4 v[142:143], off
	v_lshl_add_u64 v[142:143], v[192:193], 0, s[34:35]
	s_mov_b32 m0, s63
	s_nop 0
	global_load_lds_dwordx4 v[142:143], off
	v_lshl_add_u64 v[142:143], v[242:243], 0, s[34:35]
	s_mov_b32 m0, s64
	s_nop 0
	global_load_lds_dwordx4 v[142:143], off
	s_waitcnt vmcnt(8)
	s_waitcnt lgkmcnt(0)
	s_barrier
	s_setprio 1
	s_waitcnt lgkmcnt(0)
	v_mfma_f32_16x16x32_bf16 v[62:65], v[162:165], v[210:213], v[62:65]
	v_mfma_f32_16x16x32_bf16 v[58:61], v[170:173], v[210:213], v[58:61]
	v_mfma_f32_16x16x32_bf16 v[50:53], v[162:165], v[218:221], v[50:53]
	v_mfma_f32_16x16x32_bf16 v[42:45], v[170:173], v[218:221], v[42:45]
	v_mfma_f32_16x16x32_bf16 v[34:37], v[162:165], v[226:229], v[34:37]
	v_mfma_f32_16x16x32_bf16 v[26:29], v[170:173], v[226:229], v[26:29]
	v_mfma_f32_16x16x32_bf16 v[18:21], v[162:165], v[234:237], v[18:21]
	v_mfma_f32_16x16x32_bf16 v[10:13], v[170:173], v[234:237], v[10:13]
	v_mfma_f32_16x16x32_bf16 v[62:65], v[166:169], v[214:217], v[62:65]
	v_mfma_f32_16x16x32_bf16 v[58:61], v[174:177], v[214:217], v[58:61]
	v_mfma_f32_16x16x32_bf16 v[50:53], v[166:169], v[222:225], v[50:53]
	v_mfma_f32_16x16x32_bf16 v[42:45], v[174:177], v[222:225], v[42:45]
	v_mfma_f32_16x16x32_bf16 v[34:37], v[166:169], v[230:233], v[34:37]
	v_mfma_f32_16x16x32_bf16 v[26:29], v[174:177], v[230:233], v[26:29]
	v_mfma_f32_16x16x32_bf16 v[18:21], v[166:169], v[238:241], v[18:21]
	v_mfma_f32_16x16x32_bf16 v[10:13], v[174:177], v[238:241], v[10:13]
	s_setprio 0
	s_setprio 1
	v_mfma_f32_16x16x32_bf16 v[54:57], v[178:181], v[210:213], v[54:57]
	v_mfma_f32_16x16x32_bf16 v[46:49], v[202:205], v[210:213], v[46:49]
	v_mfma_f32_16x16x32_bf16 v[38:41], v[178:181], v[218:221], v[38:41]
	v_mfma_f32_16x16x32_bf16 v[30:33], v[202:205], v[218:221], v[30:33]
	v_mfma_f32_16x16x32_bf16 v[22:25], v[178:181], v[226:229], v[22:25]
	v_mfma_f32_16x16x32_bf16 v[14:17], v[202:205], v[226:229], v[14:17]
	v_mfma_f32_16x16x32_bf16 v[6:9], v[178:181], v[234:237], v[6:9]
	v_mfma_f32_16x16x32_bf16 v[2:5], v[202:205], v[234:237], v[2:5]
	v_mfma_f32_16x16x32_bf16 v[54:57], v[198:201], v[214:217], v[54:57]
	v_mfma_f32_16x16x32_bf16 v[46:49], v[206:209], v[214:217], v[46:49]
	v_mfma_f32_16x16x32_bf16 v[38:41], v[198:201], v[222:225], v[38:41]
	v_mfma_f32_16x16x32_bf16 v[30:33], v[206:209], v[222:225], v[30:33]
	v_mfma_f32_16x16x32_bf16 v[22:25], v[198:201], v[230:233], v[22:25]
	v_mfma_f32_16x16x32_bf16 v[14:17], v[206:209], v[230:233], v[14:17]
	v_mfma_f32_16x16x32_bf16 v[6:9], v[198:201], v[238:241], v[6:9]
	v_mfma_f32_16x16x32_bf16 v[2:5], v[206:209], v[238:241], v[2:5]
	s_setprio 0
	s_add_i32 s72, s72, 2
	s_add_u32 s54, s54, 0x100
	s_addc_u32 s55, s55, 0
	s_add_u32 s76, s76, 0x100
	s_addc_u32 s79, s79, 0
	s_add_u32 s26, s54, 0xfffc0080
	s_addc_u32 s27, s55, -1
	s_add_i32 s30, 0, 0x10000
	s_cmp_eq_u32 s72, 12
	s_cselect_b32 s59, s23, s27
	s_cselect_b32 s58, s70, s26
	s_cselect_b32 s57, s19, s79
	s_cselect_b32 s56, s71, s76
	s_add_i32 s81, 0, 0x14000
	s_cmp_gt_u32 s72, 13
	s_barrier
	s_cbranch_scc0 .LBB0_30
	s_and_b64 vcc, exec, s[14:15]
	s_cbranch_vccz .LBB0_33
	s_barrier

; #define PG8_STAGE(bufoff, gbase, voff) do { _Pragma("unroll") for (int _i = 0; _i < 2; ++_i) \
;         __builtin_amdgcn_global_load_lds((const unsigned*)((const char*)(gbase) + (voff)[_i]), (LAS unsigned*)(lds + (bufoff) + ldsw + _i * 8192), 16, 0, 0); } while (0)
; #define PG8_LDA(dst, b, h) do { _Pragma("unroll") for (int m = 0; m < 4; ++m) _Pragma("unroll") for (int k = 0; k < 2; ++k) dst[m][k] = *(const LAS bf16x8*)(lds + PG8_SA(b, h) + aoff + m * 2048 + k * 1024); } while (0)
; #define PG8_LDB(dst, b, h) do { _Pragma("unroll") for (int n = 0; n < 2; ++n) _Pragma("unroll") for (int k = 0; k < 2; ++k) dst[n][k] = *(const LAS bf16x8*)(lds + PG8_SB(b, h) + boff + n * 2048 + k * 1024); } while (0)
; #define PG8_WAIT_V(n) asm volatile("s_waitcnt vmcnt(" #n ")" ::: "memory")
; #define PG8_WAIT_L(n) asm volatile("s_waitcnt lgkmcnt(" #n ")" ::: "memory")
; template <class Epi, class Sched>
; __device__ __forceinline__ void gemm_phase(LAS unsigned char* lds, const Gemm g, const Sched& S, const Epi& E, const int tid) {
;     ...
;         const char* nA = has_next ? (const char*)g.A + (size_t)nxt.pm * tstep + (size_t)nxt.koff * 2 : cA; const char* nB = has_next ? (const char*)g.Bt + (size_t)nxt.pn * tstep + (size_t)nxt.koff * 2 : cB;
;         const int nt = cur.nt;
;         for (int t = 0; t < nt; t += 2) {
;             if constexpr (Epi::CHAIN) { if (t == 8 || t == 12) { E.mid(acc, cur, t == 8 ? 0 : 1, wr, wc, fr, fq); PG8_SCHED; } }
;             const bool last = (t == nt - 2);
;             const char* a1 = cA + (size_t)(t + 1) * kstep;
;             const char* a2 = last ? nA : cA + (size_t)(t + 2) * kstep; const char* b2 = last ? nB : cB + (size_t)(t + 2) * kstep;
;             const char* a3 = a2 + kstep; const char* b3 = b2 + kstep;
;             PG8_LDB(B0, 0, 0); PG8_LDB(B1, 0, 1); PG8_SCHED; PG8_LDA(At, 0, 0); PG8_STAGE(PG8_SA(1, 1), a1 + hstep, voffA);
;             PG8_WAIT_V(8); PG8_WAIT_L(0); PG8_BAR; PG8_MMA(0, 0, At, B0); PG8_MMA(0, 1, At, B1); PG8_BAR; PG8_SCHED;
;     ...
;         if (!(Epi::CHAIN && nxt.seg != 0))
; #pragma unroll
;         for (int a = 0; a < 2; ++a)
; #pragma unroll
;             for (int b = 0; b < 2; ++b)
; #pragma unroll
;                 for (int m = 0; m < 4; ++m)
; #pragma unroll
;                     for (int n = 0; n < 2; ++n) acc[a][b][m][n] = (f32x4){0.f, 0.f, 0.f, 0.f};
;         cur = nxt; cA = nA; cB = nB; ++ui;
.LBB0_60:
	s_ashr_i32 s55, s54, 31
	s_lshl_b64 s[26:27], s[54:55], 19
	s_add_u32 s28, s11, s26
	s_addc_u32 s30, s21, s27
	s_and_b64 s[26:27], s[6:7], exec
	s_cselect_b32 s57, s30, s65
	s_cselect_b32 s56, s28, s64
	s_ashr_i32 s53, s52, 31
	s_lshl_b64 s[26:27], s[52:53], 19
	s_add_u32 s28, s36, s26
	s_addc_u32 s30, s42, s27
	s_and_b64 s[26:27], s[6:7], exec
	s_cselect_b32 s59, s30, s67
	s_cselect_b32 s58, s28, s66
	s_add_u32 s28, s66, 0x100
	v_mov_b32_e32 v2, 0
	s_addc_u32 s53, s67, 0
	s_mov_b32 s55, -2
	s_waitcnt lgkmcnt(0)
	v_mov_b32_e32 v3, v2
	v_mov_b32_e32 v4, v2
	v_mov_b32_e32 v5, v2
	v_mov_b32_e32 v6, v2
	v_mov_b32_e32 v7, v2
	v_mov_b32_e32 v8, v2
	v_mov_b32_e32 v9, v2
	v_mov_b32_e32 v18, v2
	v_mov_b32_e32 v19, v2
	v_mov_b32_e32 v20, v2
	v_mov_b32_e32 v21, v2
	v_mov_b32_e32 v22, v2
	v_mov_b32_e32 v23, v2
	v_mov_b32_e32 v24, v2
	v_mov_b32_e32 v25, v2
	v_mov_b32_e32 v34, v2
	v_mov_b32_e32 v35, v2
	v_mov_b32_e32 v36, v2
	v_mov_b32_e32 v37, v2
	v_mov_b32_e32 v38, v2
	v_mov_b32_e32 v39, v2
	v_mov_b32_e32 v40, v2
	v_mov_b32_e32 v41, v2
	v_mov_b32_e32 v50, v2
	v_mov_b32_e32 v51, v2
	v_mov_b32_e32 v52, v2
	v_mov_b32_e32 v53, v2
	v_mov_b32_e32 v54, v2
	v_mov_b32_e32 v55, v2
	v_mov_b32_e32 v56, v2
	v_mov_b32_e32 v57, v2
	v_mov_b32_e32 v10, v2
	v_mov_b32_e32 v11, v2
	v_mov_b32_e32 v12, v2
	v_mov_b32_e32 v13, v2
	v_mov_b32_e32 v14, v2
	v_mov_b32_e32 v15, v2
	v_mov_b32_e32 v16, v2
	v_mov_b32_e32 v17, v2
	v_mov_b32_e32 v26, v2
	v_mov_b32_e32 v27, v2
	v_mov_b32_e32 v28, v2
	v_mov_b32_e32 v29, v2
	v_mov_b32_e32 v30, v2
	v_mov_b32_e32 v31, v2
	v_mov_b32_e32 v32, v2
	v_mov_b32_e32 v33, v2
	v_mov_b32_e32 v42, v2
	v_mov_b32_e32 v43, v2
	v_mov_b32_e32 v44, v2
	v_mov_b32_e32 v45, v2
	v_mov_b32_e32 v46, v2
	v_mov_b32_e32 v47, v2
	v_mov_b32_e32 v48, v2
	v_mov_b32_e32 v49, v2
	v_mov_b32_e32 v58, v2
	v_mov_b32_e32 v59, v2
	v_mov_b32_e32 v60, v2
	v_mov_b32_e32 v61, v2
	v_mov_b32_e32 v62, v2
	v_mov_b32_e32 v63, v2
	v_mov_b32_e32 v64, v2
	v_mov_b32_e32 v65, v2
	v_mov_b32_e32 v66, v2
	v_mov_b32_e32 v67, v2
	v_mov_b32_e32 v68, v2
	v_mov_b32_e32 v69, v2
	v_mov_b32_e32 v70, v2
	v_mov_b32_e32 v71, v2
	v_mov_b32_e32 v72, v2
	v_mov_b32_e32 v73, v2
	v_mov_b32_e32 v82, v2
	v_mov_b32_e32 v83, v2
	v_mov_b32_e32 v84, v2
	v_mov_b32_e32 v85, v2
	s_waitcnt vmcnt(0)
	v_mov_b32_e32 v86, v2
	v_mov_b32_e32 v87, v2
	v_mov_b32_e32 v88, v2
	v_mov_b32_e32 v89, v2
	v_mov_b32_e32 v98, v2
	v_mov_b32_e32 v99, v2
	v_mov_b32_e32 v100, v2
	v_mov_b32_e32 v101, v2
	v_mov_b32_e32 v102, v2
	v_mov_b32_e32 v103, v2
	v_mov_b32_e32 v104, v2
	v_mov_b32_e32 v105, v2
	v_mov_b32_e32 v114, v2
	v_mov_b32_e32 v115, v2
	v_mov_b32_e32 v116, v2
	v_mov_b32_e32 v117, v2
	v_mov_b32_e32 v118, v2
	v_mov_b32_e32 v119, v2
	v_mov_b32_e32 v120, v2
	v_mov_b32_e32 v121, v2
	v_mov_b32_e32 v74, v2
	v_mov_b32_e32 v75, v2
	v_mov_b32_e32 v76, v2
	v_mov_b32_e32 v77, v2
	v_mov_b32_e32 v78, v2
	v_mov_b32_e32 v79, v2
	v_mov_b32_e32 v80, v2
	v_mov_b32_e32 v81, v2
	v_mov_b32_e32 v90, v2
	v_mov_b32_e32 v91, v2
	v_mov_b32_e32 v92, v2
	v_mov_b32_e32 v93, v2
	v_mov_b32_e32 v94, v2
	v_mov_b32_e32 v95, v2
	v_mov_b32_e32 v96, v2
	v_mov_b32_e32 v97, v2
	v_mov_b32_e32 v106, v2
	v_mov_b32_e32 v107, v2
	v_mov_b32_e32 v108, v2
	v_mov_b32_e32 v109, v2
	v_mov_b32_e32 v110, v2
	v_mov_b32_e32 v111, v2
	v_mov_b32_e32 v112, v2
	v_mov_b32_e32 v113, v2
	v_mov_b32_e32 v122, v2
	v_mov_b32_e32 v123, v2
	v_mov_b32_e32 v124, v2
	v_mov_b32_e32 v125, v2
	v_mov_b32_e32 v126, v2
	v_mov_b32_e32 v127, v2
	v_mov_b32_e32 v128, v2
	v_mov_b32_e32 v129, v2
	s_add_u32 s66, s64, 0x100
	s_addc_u32 s67, s65, 0
	s_add_i32 s26, 0, 0x10000
	s_cmp_eq_u32 s55, 12
	s_cselect_b32 s71, s57, s67
	s_cselect_b32 s70, s56, s66
	s_cselect_b32 s69, s59, s53
	s_cselect_b32 s68, s58, s28
	s_add_i32 s30, 0, 0x14000
.LBB0_61:
	v_add_u32_e32 v140, s26, v143
	ds_read_b128 v[136:139], v140
	ds_read_b128 v[156:159], v140 offset:1024
	ds_read_b128 v[160:163], v140 offset:2048
	ds_read_b128 v[164:167], v140 offset:3072
	v_add_u32_e32 v140, s30, v143
	ds_read_b128 v[168:171], v140
	ds_read_b128 v[172:175], v140 offset:1024
	ds_read_b128 v[176:179], v140 offset:2048
	ds_read_b128 v[180:183], v140 offset:3072
	v_lshl_add_u64 v[140:141], s[64:65], 0, v[132:133]
	s_add_i32 m0, s44, 0xc000
	ds_read_b128 v[198:201], v145
	ds_read_b128 v[202:205], v145 offset:1024
	ds_read_b128 v[206:209], v145 offset:2048
	ds_read_b128 v[210:213], v145 offset:3072
	ds_read_b128 v[214:217], v145 offset:4096
	ds_read_b128 v[218:221], v145 offset:5120
	ds_read_b128 v[222:225], v145 offset:6144
	ds_read_b128 v[226:229], v145 offset:7168
	global_load_lds_dwordx4 v[140:141], off
	v_lshl_add_u64 v[140:141], s[64:65], 0, v[134:135]
	s_add_i32 m0, s44, 0xe000
	s_nop 0
	global_load_lds_dwordx4 v[140:141], off
	s_waitcnt vmcnt(8)
	s_waitcnt lgkmcnt(0)
	s_barrier
; #define PG8_STAGE(bufoff, gbase, voff) do { _Pragma("unroll") for (int _i = 0; _i < 2; ++_i) \
;         __builtin_amdgcn_global_load_lds((const unsigned*)((const char*)(gbase) + (voff)[_i]), (LAS unsigned*)(lds + (bufoff) + ldsw + _i * 8192), 16, 0, 0); } while (0)
; #define PG8_LDA(dst, b, h) do { _Pragma("unroll") for (int m = 0; m < 4; ++m) _Pragma("unroll") for (int k = 0; k < 2; ++k) dst[m][k] = *(const LAS bf16x8*)(lds + PG8_SA(b, h) + aoff + m * 2048 + k * 1024); } while (0)
; #define PG8_MMA(ai, bj, At, Bt) do { __builtin_amdgcn_s_setprio(1); _Pragma("unroll") for (int m = 0; m < 4; ++m) _Pragma("unroll") for (int n = 0; n < 2; ++n) _Pragma("unroll") for (int k = 0; k < 2; ++k) \
;         acc[ai][bj][m][n] = __builtin_amdgcn_mfma_f32_16x16x32_bf16(Bt[n][k], At[m][k], acc[ai][bj][m][n], 0, 0, 0); __builtin_amdgcn_s_setprio(0); } while (0)
; #define PG8_WAIT_V(n) asm volatile("s_waitcnt vmcnt(" #n ")" ::: "memory")
; #define PG8_WAIT_L(n) asm volatile("s_waitcnt lgkmcnt(" #n ")" ::: "memory")
; #define PG8_BAR __builtin_amdgcn_s_barrier()
; #define PG8_SCHED __builtin_amdgcn_sched_barrier(0)
; template <class Epi, class Sched>
; __device__ __forceinline__ void gemm_phase(LAS unsigned char* lds, const Gemm g, const Sched& S, const Epi& E, const int tid) {
;     ...
;             PG8_WAIT_V(8); PG8_WAIT_L(0); PG8_BAR; PG8_MMA(0, 0, At, B0); PG8_MMA(0, 1, At, B1); PG8_BAR; PG8_SCHED;
;             PG8_LDA(At, 0, 1); PG8_STAGE(PG8_SB(0, 0), b2, voffB); PG8_STAGE(PG8_SB(0, 1), b2 + hstep, voffB); PG8_STAGE(PG8_SA(0, 0), a2, voffA);
;             PG8_WAIT_V(8); PG8_WAIT_L(0); PG8_BAR; PG8_MMA(1, 0, At, B0); PG8_MMA(1, 1, At, B1); PG8_BAR; PG8_SCHED;
	s_setprio 1
	s_waitcnt lgkmcnt(0)
	v_mfma_f32_16x16x32_bf16 v[126:129], v[136:139], v[198:201], v[126:129]
	v_mfma_f32_16x16x32_bf16 v[122:125], v[160:163], v[198:201], v[122:125]
	v_mfma_f32_16x16x32_bf16 v[110:113], v[136:139], v[206:209], v[110:113]
	v_mfma_f32_16x16x32_bf16 v[106:109], v[160:163], v[206:209], v[106:109]
	v_mfma_f32_16x16x32_bf16 v[94:97], v[136:139], v[214:217], v[94:97]
	v_mfma_f32_16x16x32_bf16 v[90:93], v[160:163], v[214:217], v[90:93]
	v_mfma_f32_16x16x32_bf16 v[78:81], v[136:139], v[222:225], v[78:81]
	v_mfma_f32_16x16x32_bf16 v[74:77], v[160:163], v[222:225], v[74:77]
	v_mfma_f32_16x16x32_bf16 v[126:129], v[156:159], v[202:205], v[126:129]
	v_mfma_f32_16x16x32_bf16 v[122:125], v[164:167], v[202:205], v[122:125]
	v_mfma_f32_16x16x32_bf16 v[110:113], v[156:159], v[210:213], v[110:113]
	v_mfma_f32_16x16x32_bf16 v[106:109], v[164:167], v[210:213], v[106:109]
	v_mfma_f32_16x16x32_bf16 v[94:97], v[156:159], v[218:221], v[94:97]
	v_mfma_f32_16x16x32_bf16 v[90:93], v[164:167], v[218:221], v[90:93]
	v_mfma_f32_16x16x32_bf16 v[78:81], v[156:159], v[226:229], v[78:81]
	v_mfma_f32_16x16x32_bf16 v[74:77], v[164:167], v[226:229], v[74:77]
	s_setprio 0
	s_setprio 1
	v_mfma_f32_16x16x32_bf16 v[118:121], v[168:171], v[198:201], v[118:121]
	v_mfma_f32_16x16x32_bf16 v[114:117], v[176:179], v[198:201], v[114:117]
	v_mfma_f32_16x16x32_bf16 v[102:105], v[168:171], v[206:209], v[102:105]
	v_mfma_f32_16x16x32_bf16 v[98:101], v[176:179], v[206:209], v[98:101]
	v_mfma_f32_16x16x32_bf16 v[86:89], v[168:171], v[214:217], v[86:89]
	v_mfma_f32_16x16x32_bf16 v[82:85], v[176:179], v[214:217], v[82:85]
	v_mfma_f32_16x16x32_bf16 v[70:73], v[168:171], v[222:225], v[70:73]
	v_mfma_f32_16x16x32_bf16 v[66:69], v[176:179], v[222:225], v[66:69]
	v_mfma_f32_16x16x32_bf16 v[118:121], v[172:175], v[202:205], v[118:121]
	v_mfma_f32_16x16x32_bf16 v[114:117], v[180:183], v[202:205], v[114:117]
	v_mfma_f32_16x16x32_bf16 v[102:105], v[172:175], v[210:213], v[102:105]
	v_mfma_f32_16x16x32_bf16 v[98:101], v[180:183], v[210:213], v[98:101]
	v_mfma_f32_16x16x32_bf16 v[86:89], v[172:175], v[218:221], v[86:89]
	v_mfma_f32_16x16x32_bf16 v[82:85], v[180:183], v[218:221], v[82:85]
	v_mfma_f32_16x16x32_bf16 v[70:73], v[172:175], v[226:229], v[70:73]
	v_mfma_f32_16x16x32_bf16 v[66:69], v[180:183], v[226:229], v[66:69]
	s_setprio 0
	s_barrier
	s_add_i32 s26, s26, s43
	v_lshl_add_u64 v[140:141], s[68:69], 0, v[0:1]
	s_mov_b32 m0, s26
	ds_read_b128 v[198:201], v145 offset:16384
	ds_read_b128 v[202:205], v145 offset:17408
	ds_read_b128 v[206:209], v145 offset:18432
	ds_read_b128 v[210:213], v145 offset:19456
	ds_read_b128 v[214:217], v145 offset:20480
	ds_read_b128 v[218:221], v145 offset:21504
	ds_read_b128 v[222:225], v145 offset:22528
	ds_read_b128 v[226:229], v145 offset:23552
	global_load_lds_dwordx4 v[140:141], off
	s_add_i32 m0, s26, 0x2000
	s_add_u32 s26, s68, 0x40000
	v_lshl_add_u64 v[192:193], s[68:69], 0, v[130:131]
	s_addc_u32 s27, s69, 0
	s_add_i32 s30, s30, s43
	global_load_lds_dwordx4 v[192:193], off
	v_lshl_add_u64 v[230:231], s[26:27], 0, v[0:1]
	s_mov_b32 m0, s30
	v_lshl_add_u64 v[232:233], s[70:71], 0, v[130:131]
	global_load_lds_dwordx4 v[230:231], off
	v_lshl_add_u64 v[230:231], s[26:27], 0, v[130:131]
	s_add_i32 m0, s30, 0x2000
	s_nop 0
	global_load_lds_dwordx4 v[230:231], off
	v_lshl_add_u64 v[230:231], s[70:71], 0, v[0:1]
	s_mov_b32 m0, s44
	s_nop 0
	global_load_lds_dwordx4 v[230:231], off
	s_mov_b32 m0, s45
	s_nop 0
	global_load_lds_dwordx4 v[232:233], off
	s_waitcnt vmcnt(8)
	s_waitcnt lgkmcnt(0)
	s_barrier
	s_setprio 1
	s_waitcnt lgkmcnt(0)
	v_mfma_f32_16x16x32_bf16 v[62:65], v[136:139], v[198:201], v[62:65]
	v_mfma_f32_16x16x32_bf16 v[58:61], v[160:163], v[198:201], v[58:61]
	v_mfma_f32_16x16x32_bf16 v[46:49], v[136:139], v[206:209], v[46:49]
	v_mfma_f32_16x16x32_bf16 v[42:45], v[160:163], v[206:209], v[42:45]
	v_mfma_f32_16x16x32_bf16 v[30:33], v[136:139], v[214:217], v[30:33]
	v_mfma_f32_16x16x32_bf16 v[26:29], v[160:163], v[214:217], v[26:29]
	v_mfma_f32_16x16x32_bf16 v[14:17], v[136:139], v[222:225], v[14:17]
	v_mfma_f32_16x16x32_bf16 v[10:13], v[160:163], v[222:225], v[10:13]
	v_mfma_f32_16x16x32_bf16 v[62:65], v[156:159], v[202:205], v[62:65]
	v_mfma_f32_16x16x32_bf16 v[58:61], v[164:167], v[202:205], v[58:61]
	v_mfma_f32_16x16x32_bf16 v[46:49], v[156:159], v[210:213], v[46:49]
	v_mfma_f32_16x16x32_bf16 v[42:45], v[164:167], v[210:213], v[42:45]
	v_mfma_f32_16x16x32_bf16 v[30:33], v[156:159], v[218:221], v[30:33]
	v_mfma_f32_16x16x32_bf16 v[26:29], v[164:167], v[218:221], v[26:29]
	v_mfma_f32_16x16x32_bf16 v[14:17], v[156:159], v[226:229], v[14:17]
	v_mfma_f32_16x16x32_bf16 v[10:13], v[164:167], v[226:229], v[10:13]
	s_setprio 0
	s_setprio 1
	v_mfma_f32_16x16x32_bf16 v[54:57], v[168:171], v[198:201], v[54:57]
	v_mfma_f32_16x16x32_bf16 v[50:53], v[176:179], v[198:201], v[50:53]
	v_mfma_f32_16x16x32_bf16 v[38:41], v[168:171], v[206:209], v[38:41]
	v_mfma_f32_16x16x32_bf16 v[34:37], v[176:179], v[206:209], v[34:37]
	v_mfma_f32_16x16x32_bf16 v[22:25], v[168:171], v[214:217], v[22:25]
	v_mfma_f32_16x16x32_bf16 v[18:21], v[176:179], v[214:217], v[18:21]
	v_mfma_f32_16x16x32_bf16 v[6:9], v[168:171], v[222:225], v[6:9]
	v_mfma_f32_16x16x32_bf16 v[2:5], v[176:179], v[222:225], v[2:5]
	v_mfma_f32_16x16x32_bf16 v[54:57], v[172:175], v[202:205], v[54:57]
	v_mfma_f32_16x16x32_bf16 v[50:53], v[180:183], v[202:205], v[50:53]
	v_mfma_f32_16x16x32_bf16 v[38:41], v[172:175], v[210:213], v[38:41]
	v_mfma_f32_16x16x32_bf16 v[34:37], v[180:183], v[210:213], v[34:37]
	v_mfma_f32_16x16x32_bf16 v[22:25], v[172:175], v[218:221], v[22:25]
	v_mfma_f32_16x16x32_bf16 v[18:21], v[180:183], v[218:221], v[18:21]
	v_mfma_f32_16x16x32_bf16 v[6:9], v[172:175], v[226:229], v[6:9]
	v_mfma_f32_16x16x32_bf16 v[2:5], v[180:183], v[226:229], v[2:5]
	s_setprio 0
	s_barrier
; #define PG8_STAGE(bufoff, gbase, voff) do { _Pragma("unroll") for (int _i = 0; _i < 2; ++_i) \
;         __builtin_amdgcn_global_load_lds((const unsigned*)((const char*)(gbase) + (voff)[_i]), (LAS unsigned*)(lds + (bufoff) + ldsw + _i * 8192), 16, 0, 0); } while (0)
; #define PG8_LDA(dst, b, h) do { _Pragma("unroll") for (int m = 0; m < 4; ++m) _Pragma("unroll") for (int k = 0; k < 2; ++k) dst[m][k] = *(const LAS bf16x8*)(lds + PG8_SA(b, h) + aoff + m * 2048 + k * 1024); } while (0)
; #define PG8_LDB(dst, b, h) do { _Pragma("unroll") for (int n = 0; n < 2; ++n) _Pragma("unroll") for (int k = 0; k < 2; ++k) dst[n][k] = *(const LAS bf16x8*)(lds + PG8_SB(b, h) + boff + n * 2048 + k * 1024); } while (0)
; #define PG8_MMA(ai, bj, At, Bt) do { __builtin_amdgcn_s_setprio(1); _Pragma("unroll") for (int m = 0; m < 4; ++m) _Pragma("unroll") for (int n = 0; n < 2; ++n) _Pragma("unroll") for (int k = 0; k < 2; ++k) \
;         acc[ai][bj][m][n] = __builtin_amdgcn_mfma_f32_16x16x32_bf16(Bt[n][k], At[m][k], acc[ai][bj][m][n], 0, 0, 0); __builtin_amdgcn_s_setprio(0); } while (0)
; #define PG8_WAIT_V(n) asm volatile("s_waitcnt vmcnt(" #n ")" ::: "memory")
; #define PG8_WAIT_L(n) asm volatile("s_waitcnt lgkmcnt(" #n ")" ::: "memory")
; #define PG8_BAR __builtin_amdgcn_s_barrier()
; #define PG8_SCHED __builtin_amdgcn_sched_barrier(0)
; template <class Epi, class Sched>
; __device__ __forceinline__ void gemm_phase(LAS unsigned char* lds, const Gemm g, const Sched& S, const Epi& E, const int tid) {
;     ...
;             PG8_LDB(B0, 1, 0); PG8_LDB(B1, 1, 1); PG8_SCHED; PG8_LDA(At, 1, 0); PG8_STAGE(PG8_SA(0, 1), a2 + hstep, voffA);
;             PG8_WAIT_V(8); PG8_WAIT_L(0); PG8_BAR; PG8_MMA(0, 0, At, B0); PG8_MMA(0, 1, At, B1); PG8_BAR; PG8_SCHED;
	s_add_i32 s30, 0, 0x18000
	s_add_i32 s61, 0, 0x1c000
	v_add_u32_e32 v164, s30, v143
	v_add_u32_e32 v180, s61, v143
	ds_read_b128 v[136:139], v164
	ds_read_b128 v[156:159], v164 offset:1024
	ds_read_b128 v[160:163], v164 offset:2048
	ds_read_b128 v[164:167], v164 offset:3072
	ds_read_b128 v[168:171], v180
	ds_read_b128 v[172:175], v180 offset:1024
	ds_read_b128 v[176:179], v180 offset:2048
	ds_read_b128 v[180:183], v180 offset:3072
	s_add_u32 s26, s70, 0x40000
	s_addc_u32 s27, s71, 0
	s_mov_b32 m0, s76
	v_lshl_add_u64 v[234:235], s[26:27], 0, v[0:1]
	ds_read_b128 v[198:201], v145 offset:32768
	ds_read_b128 v[202:205], v145 offset:33792
	ds_read_b128 v[206:209], v145 offset:34816
	ds_read_b128 v[210:213], v145 offset:35840
	ds_read_b128 v[214:217], v145 offset:36864
	ds_read_b128 v[218:221], v145 offset:37888
	ds_read_b128 v[222:225], v145 offset:38912
	ds_read_b128 v[226:229], v145 offset:39936
	global_load_lds_dwordx4 v[234:235], off
	v_lshl_add_u64 v[234:235], s[26:27], 0, v[130:131]
	s_mov_b32 m0, s79
	s_nop 0
	global_load_lds_dwordx4 v[234:235], off
	s_waitcnt vmcnt(8)
	s_waitcnt lgkmcnt(0)
	s_barrier
	s_setprio 1
	s_waitcnt lgkmcnt(0)
	v_mfma_f32_16x16x32_bf16 v[126:129], v[136:139], v[198:201], v[126:129]
	v_mfma_f32_16x16x32_bf16 v[122:125], v[160:163], v[198:201], v[122:125]
	v_mfma_f32_16x16x32_bf16 v[110:113], v[136:139], v[206:209], v[110:113]
	v_mfma_f32_16x16x32_bf16 v[106:109], v[160:163], v[206:209], v[106:109]
	v_mfma_f32_16x16x32_bf16 v[94:97], v[136:139], v[214:217], v[94:97]
	v_mfma_f32_16x16x32_bf16 v[90:93], v[160:163], v[214:217], v[90:93]
	v_mfma_f32_16x16x32_bf16 v[78:81], v[136:139], v[222:225], v[78:81]
	v_mfma_f32_16x16x32_bf16 v[74:77], v[160:163], v[222:225], v[74:77]
	v_mfma_f32_16x16x32_bf16 v[126:129], v[156:159], v[202:205], v[126:129]
	v_mfma_f32_16x16x32_bf16 v[122:125], v[164:167], v[202:205], v[122:125]
	v_mfma_f32_16x16x32_bf16 v[110:113], v[156:159], v[210:213], v[110:113]
	v_mfma_f32_16x16x32_bf16 v[106:109], v[164:167], v[210:213], v[106:109]
	v_mfma_f32_16x16x32_bf16 v[94:97], v[156:159], v[218:221], v[94:97]
	v_mfma_f32_16x16x32_bf16 v[90:93], v[164:167], v[218:221], v[90:93]
	v_mfma_f32_16x16x32_bf16 v[78:81], v[156:159], v[226:229], v[78:81]
	v_mfma_f32_16x16x32_bf16 v[74:77], v[164:167], v[226:229], v[74:77]
	s_setprio 0
	s_setprio 1
	v_mfma_f32_16x16x32_bf16 v[118:121], v[168:171], v[198:201], v[118:121]
	v_mfma_f32_16x16x32_bf16 v[114:117], v[176:179], v[198:201], v[114:117]
	v_mfma_f32_16x16x32_bf16 v[102:105], v[168:171], v[206:209], v[102:105]
	v_mfma_f32_16x16x32_bf16 v[98:101], v[176:179], v[206:209], v[98:101]
	v_mfma_f32_16x16x32_bf16 v[86:89], v[168:171], v[214:217], v[86:89]
	v_mfma_f32_16x16x32_bf16 v[82:85], v[176:179], v[214:217], v[82:85]
	v_mfma_f32_16x16x32_bf16 v[70:73], v[168:171], v[222:225], v[70:73]
	v_mfma_f32_16x16x32_bf16 v[66:69], v[176:179], v[222:225], v[66:69]
	v_mfma_f32_16x16x32_bf16 v[118:121], v[172:175], v[202:205], v[118:121]
	v_mfma_f32_16x16x32_bf16 v[114:117], v[180:183], v[202:205], v[114:117]
	v_mfma_f32_16x16x32_bf16 v[102:105], v[172:175], v[210:213], v[102:105]
	v_mfma_f32_16x16x32_bf16 v[98:101], v[180:183], v[210:213], v[98:101]
	v_mfma_f32_16x16x32_bf16 v[86:89], v[172:175], v[218:221], v[86:89]
	v_mfma_f32_16x16x32_bf16 v[82:85], v[180:183], v[218:221], v[82:85]
	v_mfma_f32_16x16x32_bf16 v[70:73], v[172:175], v[226:229], v[70:73]
	v_mfma_f32_16x16x32_bf16 v[66:69], v[180:183], v[226:229], v[66:69]
	s_setprio 0
	s_barrier
; #define PG8_STAGE(bufoff, gbase, voff) do { _Pragma("unroll") for (int _i = 0; _i < 2; ++_i) \
;         __builtin_amdgcn_global_load_lds((const unsigned*)((const char*)(gbase) + (voff)[_i]), (LAS unsigned*)(lds + (bufoff) + ldsw + _i * 8192), 16, 0, 0); } while (0)
; #define PG8_LDA(dst, b, h) do { _Pragma("unroll") for (int m = 0; m < 4; ++m) _Pragma("unroll") for (int k = 0; k < 2; ++k) dst[m][k] = *(const LAS bf16x8*)(lds + PG8_SA(b, h) + aoff + m * 2048 + k * 1024); } while (0)
; #define PG8_MMA(ai, bj, At, Bt) do { __builtin_amdgcn_s_setprio(1); _Pragma("unroll") for (int m = 0; m < 4; ++m) _Pragma("unroll") for (int n = 0; n < 2; ++n) _Pragma("unroll") for (int k = 0; k < 2; ++k) \
;         acc[ai][bj][m][n] = __builtin_amdgcn_mfma_f32_16x16x32_bf16(Bt[n][k], At[m][k], acc[ai][bj][m][n], 0, 0, 0); __builtin_amdgcn_s_setprio(0); } while (0)
; #define PG8_WAIT_V(n) asm volatile("s_waitcnt vmcnt(" #n ")" ::: "memory")
; #define PG8_WAIT_L(n) asm volatile("s_waitcnt lgkmcnt(" #n ")" ::: "memory")
; #define PG8_BAR __builtin_amdgcn_s_barrier()
; #define PG8_SCHED __builtin_amdgcn_sched_barrier(0)
; template <class Epi, class Sched>
; __device__ __forceinline__ void gemm_phase(LAS unsigned char* lds, const Gemm g, const Sched& S, const Epi& E, const int tid) {
;     ...
;         for (int t = 0; t < nt; t += 2) {
;             if constexpr (Epi::CHAIN) { if (t == 8 || t == 12) { E.mid(acc, cur, t == 8 ? 0 : 1, wr, wc, fr, fq); PG8_SCHED; } }
;             const bool last = (t == nt - 2);
;             const char* a1 = cA + (size_t)(t + 1) * kstep;
;             const char* a2 = last ? nA : cA + (size_t)(t + 2) * kstep; const char* b2 = last ? nB : cB + (size_t)(t + 2) * kstep;
;             const char* a3 = a2 + kstep; const char* b3 = b2 + kstep;
;     ...
;             PG8_LDA(At, 1, 1); PG8_STAGE(PG8_SB(1, 0), b3, voffB); PG8_STAGE(PG8_SB(1, 1), b3 + hstep, voffB); PG8_STAGE(PG8_SA(1, 0), a3, voffA);
;             PG8_WAIT_V(8); PG8_WAIT_L(0); PG8_BAR; PG8_MMA(1, 0, At, B0); PG8_MMA(1, 1, At, B1); PG8_BAR; PG8_SCHED;
;         }
	s_add_i32 s26, s30, s43
	v_lshl_add_u64 v[140:141], v[140:141], 0, s[34:35]
	s_mov_b32 m0, s26
	ds_read_b128 v[198:201], v145 offset:49152
	ds_read_b128 v[202:205], v145 offset:50176
	ds_read_b128 v[206:209], v145 offset:51200
	ds_read_b128 v[210:213], v145 offset:52224
	ds_read_b128 v[214:217], v145 offset:53248
	ds_read_b128 v[218:221], v145 offset:54272
	ds_read_b128 v[222:225], v145 offset:55296
	ds_read_b128 v[226:229], v145 offset:56320
	global_load_lds_dwordx4 v[140:141], off
	s_add_i32 m0, s26, 0x2000
	s_add_u32 s26, s68, 0x40080
	v_lshl_add_u64 v[140:141], v[192:193], 0, s[34:35]
	s_addc_u32 s27, s69, 0
	s_add_i32 s30, s61, s43
	global_load_lds_dwordx4 v[140:141], off
	v_lshl_add_u64 v[140:141], s[26:27], 0, v[0:1]
	s_mov_b32 m0, s30
	s_nop 0
	global_load_lds_dwordx4 v[140:141], off
	v_lshl_add_u64 v[140:141], s[26:27], 0, v[130:131]
	s_add_i32 m0, s30, 0x2000
	s_nop 0
	global_load_lds_dwordx4 v[140:141], off
	v_lshl_add_u64 v[140:141], v[230:231], 0, s[34:35]
	s_mov_b32 m0, s84
	s_nop 0
	global_load_lds_dwordx4 v[140:141], off
	v_lshl_add_u64 v[140:141], v[232:233], 0, s[34:35]
	s_mov_b32 m0, s85
	s_nop 0
	global_load_lds_dwordx4 v[140:141], off
	s_waitcnt vmcnt(8)
	s_waitcnt lgkmcnt(0)
	s_barrier
	s_setprio 1
	s_waitcnt lgkmcnt(0)
	v_mfma_f32_16x16x32_bf16 v[62:65], v[136:139], v[198:201], v[62:65]
	v_mfma_f32_16x16x32_bf16 v[58:61], v[160:163], v[198:201], v[58:61]
	v_mfma_f32_16x16x32_bf16 v[46:49], v[136:139], v[206:209], v[46:49]
	v_mfma_f32_16x16x32_bf16 v[42:45], v[160:163], v[206:209], v[42:45]
	v_mfma_f32_16x16x32_bf16 v[30:33], v[136:139], v[214:217], v[30:33]
	v_mfma_f32_16x16x32_bf16 v[26:29], v[160:163], v[214:217], v[26:29]
	v_mfma_f32_16x16x32_bf16 v[14:17], v[136:139], v[222:225], v[14:17]
	v_mfma_f32_16x16x32_bf16 v[10:13], v[160:163], v[222:225], v[10:13]
	v_mfma_f32_16x16x32_bf16 v[62:65], v[156:159], v[202:205], v[62:65]
	v_mfma_f32_16x16x32_bf16 v[58:61], v[164:167], v[202:205], v[58:61]
	v_mfma_f32_16x16x32_bf16 v[46:49], v[156:159], v[210:213], v[46:49]
	v_mfma_f32_16x16x32_bf16 v[42:45], v[164:167], v[210:213], v[42:45]
	v_mfma_f32_16x16x32_bf16 v[30:33], v[156:159], v[218:221], v[30:33]
	v_mfma_f32_16x16x32_bf16 v[26:29], v[164:167], v[218:221], v[26:29]
	v_mfma_f32_16x16x32_bf16 v[14:17], v[156:159], v[226:229], v[14:17]
	v_mfma_f32_16x16x32_bf16 v[10:13], v[164:167], v[226:229], v[10:13]
	s_setprio 0
	s_setprio 1
	v_mfma_f32_16x16x32_bf16 v[54:57], v[168:171], v[198:201], v[54:57]
	v_mfma_f32_16x16x32_bf16 v[50:53], v[176:179], v[198:201], v[50:53]
	v_mfma_f32_16x16x32_bf16 v[38:41], v[168:171], v[206:209], v[38:41]
	v_mfma_f32_16x16x32_bf16 v[34:37], v[176:179], v[206:209], v[34:37]
	v_mfma_f32_16x16x32_bf16 v[22:25], v[168:171], v[214:217], v[22:25]
	v_mfma_f32_16x16x32_bf16 v[18:21], v[176:179], v[214:217], v[18:21]
	v_mfma_f32_16x16x32_bf16 v[6:9], v[168:171], v[222:225], v[6:9]
	v_mfma_f32_16x16x32_bf16 v[2:5], v[176:179], v[222:225], v[2:5]
	v_mfma_f32_16x16x32_bf16 v[54:57], v[172:175], v[202:205], v[54:57]
	v_mfma_f32_16x16x32_bf16 v[50:53], v[180:183], v[202:205], v[50:53]
	v_mfma_f32_16x16x32_bf16 v[38:41], v[172:175], v[210:213], v[38:41]
	v_mfma_f32_16x16x32_bf16 v[34:37], v[180:183], v[210:213], v[34:37]
	v_mfma_f32_16x16x32_bf16 v[22:25], v[172:175], v[218:221], v[22:25]
	v_mfma_f32_16x16x32_bf16 v[18:21], v[180:183], v[218:221], v[18:21]
	v_mfma_f32_16x16x32_bf16 v[6:9], v[172:175], v[226:229], v[6:9]
	v_mfma_f32_16x16x32_bf16 v[2:5], v[180:183], v[226:229], v[2:5]
	s_setprio 0
	s_add_i32 s55, s55, 2
	s_add_u32 s28, s28, 0x100
	s_addc_u32 s53, s53, 0
	s_mov_b64 s[64:65], s[66:67]
	s_add_u32 s66, s64, 0x100
	s_addc_u32 s67, s65, 0
	s_add_i32 s26, 0, 0x10000
	s_cmp_eq_u32 s55, 12
	s_cselect_b32 s71, s57, s67
	s_cselect_b32 s70, s56, s66
	s_cselect_b32 s69, s59, s53
	s_cselect_b32 s68, s58, s28
	s_add_i32 s30, 0, 0x14000
	s_cmp_gt_u32 s55, 13
	s_barrier
	s_cbranch_scc0 .LBB0_61
	s_and_b64 vcc, exec, s[50:51]
	s_cbranch_vccz .LBB0_64
	s_barrier

; #define PG8_STAGE(bufoff, gbase, voff) do { _Pragma("unroll") for (int _i = 0; _i < 2; ++_i) \
;         __builtin_amdgcn_global_load_lds((const unsigned*)((const char*)(gbase) + (voff)[_i]), (LAS unsigned*)(lds + (bufoff) + ldsw + _i * 8192), 16, 0, 0); } while (0)
; #define PG8_LDA(dst, b, h) do { _Pragma("unroll") for (int m = 0; m < 4; ++m) _Pragma("unroll") for (int k = 0; k < 2; ++k) dst[m][k] = *(const LAS bf16x8*)(lds + PG8_SA(b, h) + aoff + m * 2048 + k * 1024); } while (0)
; #define PG8_LDB(dst, b, h) do { _Pragma("unroll") for (int n = 0; n < 2; ++n) _Pragma("unroll") for (int k = 0; k < 2; ++k) dst[n][k] = *(const LAS bf16x8*)(lds + PG8_SB(b, h) + boff + n * 2048 + k * 1024); } while (0)
; #define PG8_WAIT_V(n) asm volatile("s_waitcnt vmcnt(" #n ")" ::: "memory")
; #define PG8_WAIT_L(n) asm volatile("s_waitcnt lgkmcnt(" #n ")" ::: "memory")
; template <class Epi, class Sched>
; __device__ __forceinline__ void gemm_phase(LAS unsigned char* lds, const Gemm g, const Sched& S, const Epi& E, const int tid) {
;     ...
;         const char* nA = has_next ? (const char*)g.A + (size_t)nxt.pm * tstep + (size_t)nxt.koff * 2 : cA; const char* nB = has_next ? (const char*)g.Bt + (size_t)nxt.pn * tstep + (size_t)nxt.koff * 2 : cB;
;         const int nt = cur.nt;
;         for (int t = 0; t < nt; t += 2) {
;             if constexpr (Epi::CHAIN) { if (t == 8 || t == 12) { E.mid(acc, cur, t == 8 ? 0 : 1, wr, wc, fr, fq); PG8_SCHED; } }
;             const bool last = (t == nt - 2);
;             const char* a1 = cA + (size_t)(t + 1) * kstep;
;             const char* a2 = last ? nA : cA + (size_t)(t + 2) * kstep; const char* b2 = last ? nB : cB + (size_t)(t + 2) * kstep;
;             const char* a3 = a2 + kstep; const char* b3 = b2 + kstep;
;             PG8_LDB(B0, 0, 0); PG8_LDB(B1, 0, 1); PG8_SCHED; PG8_LDA(At, 0, 0); PG8_STAGE(PG8_SA(1, 1), a1 + hstep, voffA);
;             PG8_WAIT_V(8); PG8_WAIT_L(0); PG8_BAR; PG8_MMA(0, 0, At, B0); PG8_MMA(0, 1, At, B1); PG8_BAR; PG8_SCHED;
;     ...
;         if (!(Epi::CHAIN && nxt.seg != 0))
; #pragma unroll
;         for (int a = 0; a < 2; ++a)
; #pragma unroll
;             for (int b = 0; b < 2; ++b)
; #pragma unroll
;                 for (int m = 0; m < 4; ++m)
; #pragma unroll
;                     for (int n = 0; n < 2; ++n) acc[a][b][m][n] = (f32x4){0.f, 0.f, 0.f, 0.f};
;         cur = nxt; cA = nA; cB = nB; ++ui;
.LBB0_238:
	s_ashr_i32 s57, s56, 31
	s_lshl_b64 s[58:59], s[56:57], 19
	s_add_u32 s58, s71, s58
	s_addc_u32 s59, s36, s59
	s_and_b64 s[60:61], s[6:7], exec
	s_cselect_b32 s28, s59, s63
	s_cselect_b32 s57, s58, s62
	s_ashr_i32 s55, s54, 31
	s_lshl_b64 s[60:61], s[54:55], 19
	s_add_u32 s60, s86, s60
	s_addc_u32 s61, s42, s61
	s_and_b64 s[68:69], s[6:7], exec
	s_cselect_b32 s55, s61, s65
	s_cselect_b32 s67, s60, s64
	s_add_u32 s62, s62, 0x40080
	s_addc_u32 s63, s63, 0
	s_add_u32 vcc_lo, s64, 0x100
	v_mov_b32_e32 v2, 0
	s_addc_u32 vcc_hi, s65, 0
	s_mov_b32 s72, -2
	v_mov_b32_e32 v3, v2
	v_mov_b32_e32 v4, v2
	v_mov_b32_e32 v5, v2
	v_mov_b32_e32 v6, v2
	v_mov_b32_e32 v7, v2
	v_mov_b32_e32 v8, v2
	v_mov_b32_e32 v9, v2
	v_mov_b32_e32 v18, v2
	v_mov_b32_e32 v19, v2
	v_mov_b32_e32 v20, v2
	v_mov_b32_e32 v21, v2
	v_mov_b32_e32 v22, v2
	v_mov_b32_e32 v23, v2
	v_mov_b32_e32 v24, v2
	v_mov_b32_e32 v25, v2
	v_mov_b32_e32 v34, v2
	v_mov_b32_e32 v35, v2
	v_mov_b32_e32 v36, v2
	v_mov_b32_e32 v37, v2
	v_mov_b32_e32 v38, v2
	v_mov_b32_e32 v39, v2
	v_mov_b32_e32 v40, v2
	v_mov_b32_e32 v41, v2
	v_mov_b32_e32 v50, v2
	v_mov_b32_e32 v51, v2
	v_mov_b32_e32 v52, v2
	v_mov_b32_e32 v53, v2
	v_mov_b32_e32 v54, v2
	v_mov_b32_e32 v55, v2
	v_mov_b32_e32 v56, v2
	v_mov_b32_e32 v57, v2
	v_mov_b32_e32 v10, v2
	v_mov_b32_e32 v11, v2
	v_mov_b32_e32 v12, v2
	v_mov_b32_e32 v13, v2
	v_mov_b32_e32 v14, v2
	v_mov_b32_e32 v15, v2
	v_mov_b32_e32 v16, v2
	v_mov_b32_e32 v17, v2
	v_mov_b32_e32 v26, v2
	v_mov_b32_e32 v27, v2
	v_mov_b32_e32 v28, v2
	v_mov_b32_e32 v29, v2
	v_mov_b32_e32 v30, v2
	v_mov_b32_e32 v31, v2
	v_mov_b32_e32 v32, v2
	v_mov_b32_e32 v33, v2
	v_mov_b32_e32 v42, v2
	v_mov_b32_e32 v43, v2
	v_mov_b32_e32 v44, v2
	v_mov_b32_e32 v45, v2
	v_mov_b32_e32 v46, v2
	v_mov_b32_e32 v47, v2
	v_mov_b32_e32 v48, v2
	v_mov_b32_e32 v49, v2
	v_mov_b32_e32 v58, v2
	v_mov_b32_e32 v59, v2
	v_mov_b32_e32 v60, v2
	v_mov_b32_e32 v61, v2
	v_mov_b32_e32 v62, v2
	v_mov_b32_e32 v63, v2
	v_mov_b32_e32 v64, v2
	v_mov_b32_e32 v65, v2
	v_mov_b32_e32 v66, v2
	v_mov_b32_e32 v67, v2
	v_mov_b32_e32 v68, v2
	v_mov_b32_e32 v69, v2
	v_mov_b32_e32 v70, v2
	v_mov_b32_e32 v71, v2
	v_mov_b32_e32 v72, v2
	v_mov_b32_e32 v73, v2
	v_mov_b32_e32 v82, v2
	v_mov_b32_e32 v83, v2
	v_mov_b32_e32 v84, v2
	v_mov_b32_e32 v85, v2
	s_waitcnt vmcnt(0)
	v_mov_b32_e32 v86, v2
	v_mov_b32_e32 v87, v2
	v_mov_b32_e32 v88, v2
	v_mov_b32_e32 v89, v2
	v_mov_b32_e32 v98, v2
	v_mov_b32_e32 v99, v2
	v_mov_b32_e32 v100, v2
	v_mov_b32_e32 v101, v2
	v_mov_b32_e32 v102, v2
	v_mov_b32_e32 v103, v2
	v_mov_b32_e32 v104, v2
	v_mov_b32_e32 v105, v2
	v_mov_b32_e32 v114, v2
	v_mov_b32_e32 v115, v2
	v_mov_b32_e32 v116, v2
	v_mov_b32_e32 v117, v2
	v_mov_b32_e32 v118, v2
	v_mov_b32_e32 v119, v2
	v_mov_b32_e32 v120, v2
	v_mov_b32_e32 v121, v2
	v_mov_b32_e32 v74, v2
	v_mov_b32_e32 v75, v2
	v_mov_b32_e32 v76, v2
	v_mov_b32_e32 v77, v2
	v_mov_b32_e32 v78, v2
	v_mov_b32_e32 v79, v2
	v_mov_b32_e32 v80, v2
	v_mov_b32_e32 v81, v2
	v_mov_b32_e32 v90, v2
	v_mov_b32_e32 v91, v2
	v_mov_b32_e32 v92, v2
	v_mov_b32_e32 v93, v2
	v_mov_b32_e32 v94, v2
	v_mov_b32_e32 v95, v2
	v_mov_b32_e32 v96, v2
	v_mov_b32_e32 v97, v2
	v_mov_b32_e32 v106, v2
	v_mov_b32_e32 v107, v2
	v_mov_b32_e32 v108, v2
	v_mov_b32_e32 v109, v2
	v_mov_b32_e32 v110, v2
	v_mov_b32_e32 v111, v2
	v_mov_b32_e32 v112, v2
	v_mov_b32_e32 v113, v2
	v_mov_b32_e32 v122, v2
	v_mov_b32_e32 v123, v2
	v_mov_b32_e32 v124, v2
	v_mov_b32_e32 v125, v2
	v_mov_b32_e32 v126, v2
	v_mov_b32_e32 v127, v2
	v_mov_b32_e32 v128, v2
	v_mov_b32_e32 v129, v2
	s_add_u32 s26, s62, 0xfffc0080
	s_addc_u32 s27, s63, -1
	s_add_i32 s95, 0, 0x10000
	s_cmp_eq_u32 s72, 12
	s_cselect_b32 s69, s28, s27
	s_cselect_b32 s68, s57, s26
	s_cselect_b32 s65, s55, vcc_hi
	s_cselect_b32 s64, s67, vcc_lo
	s_add_i32 s30, 0, 0x14000
.LBB0_239:
	v_add_u32_e32 v0, s95, v198
	ds_read_b128 v[164:167], v0
	ds_read_b128 v[168:171], v0 offset:1024
	ds_read_b128 v[172:175], v0 offset:2048
	ds_read_b128 v[176:179], v0 offset:3072
	v_add_u32_e32 v0, s30, v198
	ds_read_b128 v[180:183], v0
	ds_read_b128 v[202:205], v0 offset:1024
	ds_read_b128 v[206:209], v0 offset:2048
	ds_read_b128 v[210:213], v0 offset:3072
	v_lshl_add_u64 v[246:247], s[62:63], 0, v[156:157]
	s_add_i32 m0, s85, 0xc000
	ds_read_b128 v[214:217], v201
	ds_read_b128 v[218:221], v201 offset:1024
	ds_read_b128 v[222:225], v201 offset:2048
	ds_read_b128 v[226:229], v201 offset:3072
	ds_read_b128 v[230:233], v201 offset:4096
	ds_read_b128 v[234:237], v201 offset:5120
	ds_read_b128 v[238:241], v201 offset:6144
	ds_read_b128 v[242:245], v201 offset:7168
	global_load_lds_dwordx4 v[246:247], off
	v_lshl_add_u64 v[246:247], s[62:63], 0, v[158:159]
	s_add_i32 m0, s85, 0xe000
	s_nop 0
	global_load_lds_dwordx4 v[246:247], off
	s_waitcnt vmcnt(8)
	s_waitcnt lgkmcnt(0)
	s_barrier
; #define PG8_STAGE(bufoff, gbase, voff) do { _Pragma("unroll") for (int _i = 0; _i < 2; ++_i) \
;         __builtin_amdgcn_global_load_lds((const unsigned*)((const char*)(gbase) + (voff)[_i]), (LAS unsigned*)(lds + (bufoff) + ldsw + _i * 8192), 16, 0, 0); } while (0)
; #define PG8_LDA(dst, b, h) do { _Pragma("unroll") for (int m = 0; m < 4; ++m) _Pragma("unroll") for (int k = 0; k < 2; ++k) dst[m][k] = *(const LAS bf16x8*)(lds + PG8_SA(b, h) + aoff + m * 2048 + k * 1024); } while (0)
; #define PG8_MMA(ai, bj, At, Bt) do { __builtin_amdgcn_s_setprio(1); _Pragma("unroll") for (int m = 0; m < 4; ++m) _Pragma("unroll") for (int n = 0; n < 2; ++n) _Pragma("unroll") for (int k = 0; k < 2; ++k) \
;         acc[ai][bj][m][n] = __builtin_amdgcn_mfma_f32_16x16x32_bf16(Bt[n][k], At[m][k], acc[ai][bj][m][n], 0, 0, 0); __builtin_amdgcn_s_setprio(0); } while (0)
; #define PG8_WAIT_V(n) asm volatile("s_waitcnt vmcnt(" #n ")" ::: "memory")
; #define PG8_WAIT_L(n) asm volatile("s_waitcnt lgkmcnt(" #n ")" ::: "memory")
; #define PG8_BAR __builtin_amdgcn_s_barrier()
; #define PG8_SCHED __builtin_amdgcn_sched_barrier(0)
; template <class Epi, class Sched>
; __device__ __forceinline__ void gemm_phase(LAS unsigned char* lds, const Gemm g, const Sched& S, const Epi& E, const int tid) {
;     ...
;             PG8_WAIT_V(8); PG8_WAIT_L(0); PG8_BAR; PG8_MMA(0, 0, At, B0); PG8_MMA(0, 1, At, B1); PG8_BAR; PG8_SCHED;
;             PG8_LDA(At, 0, 1); PG8_STAGE(PG8_SB(0, 0), b2, voffB); PG8_STAGE(PG8_SB(0, 1), b2 + hstep, voffB); PG8_STAGE(PG8_SA(0, 0), a2, voffA);
;             PG8_WAIT_V(8); PG8_WAIT_L(0); PG8_BAR; PG8_MMA(1, 0, At, B0); PG8_MMA(1, 1, At, B1); PG8_BAR; PG8_SCHED;
	s_setprio 1
	s_waitcnt lgkmcnt(0)
	v_mfma_f32_16x16x32_bf16 v[126:129], v[164:167], v[214:217], v[126:129]
	v_mfma_f32_16x16x32_bf16 v[122:125], v[172:175], v[214:217], v[122:125]
	v_mfma_f32_16x16x32_bf16 v[110:113], v[164:167], v[222:225], v[110:113]
	v_mfma_f32_16x16x32_bf16 v[106:109], v[172:175], v[222:225], v[106:109]
	v_mfma_f32_16x16x32_bf16 v[94:97], v[164:167], v[230:233], v[94:97]
	v_mfma_f32_16x16x32_bf16 v[90:93], v[172:175], v[230:233], v[90:93]
	v_mfma_f32_16x16x32_bf16 v[78:81], v[164:167], v[238:241], v[78:81]
	v_mfma_f32_16x16x32_bf16 v[74:77], v[172:175], v[238:241], v[74:77]
	v_mfma_f32_16x16x32_bf16 v[126:129], v[168:171], v[218:221], v[126:129]
	v_mfma_f32_16x16x32_bf16 v[122:125], v[176:179], v[218:221], v[122:125]
	v_mfma_f32_16x16x32_bf16 v[110:113], v[168:171], v[226:229], v[110:113]
	v_mfma_f32_16x16x32_bf16 v[106:109], v[176:179], v[226:229], v[106:109]
	v_mfma_f32_16x16x32_bf16 v[94:97], v[168:171], v[234:237], v[94:97]
	v_mfma_f32_16x16x32_bf16 v[90:93], v[176:179], v[234:237], v[90:93]
	v_mfma_f32_16x16x32_bf16 v[78:81], v[168:171], v[242:245], v[78:81]
	v_mfma_f32_16x16x32_bf16 v[74:77], v[176:179], v[242:245], v[74:77]
	s_setprio 0
	s_setprio 1
	v_mfma_f32_16x16x32_bf16 v[118:121], v[180:183], v[214:217], v[118:121]
	v_mfma_f32_16x16x32_bf16 v[114:117], v[206:209], v[214:217], v[114:117]
	v_mfma_f32_16x16x32_bf16 v[102:105], v[180:183], v[222:225], v[102:105]
	v_mfma_f32_16x16x32_bf16 v[98:101], v[206:209], v[222:225], v[98:101]
	v_mfma_f32_16x16x32_bf16 v[86:89], v[180:183], v[230:233], v[86:89]
	v_mfma_f32_16x16x32_bf16 v[82:85], v[206:209], v[230:233], v[82:85]
	v_mfma_f32_16x16x32_bf16 v[70:73], v[180:183], v[238:241], v[70:73]
	v_mfma_f32_16x16x32_bf16 v[66:69], v[206:209], v[238:241], v[66:69]
	v_mfma_f32_16x16x32_bf16 v[118:121], v[202:205], v[218:221], v[118:121]
	v_mfma_f32_16x16x32_bf16 v[114:117], v[210:213], v[218:221], v[114:117]
	v_mfma_f32_16x16x32_bf16 v[102:105], v[202:205], v[226:229], v[102:105]
	v_mfma_f32_16x16x32_bf16 v[98:101], v[210:213], v[226:229], v[98:101]
	v_mfma_f32_16x16x32_bf16 v[86:89], v[202:205], v[234:237], v[86:89]
	v_mfma_f32_16x16x32_bf16 v[82:85], v[210:213], v[234:237], v[82:85]
	v_mfma_f32_16x16x32_bf16 v[70:73], v[202:205], v[242:245], v[70:73]
	v_mfma_f32_16x16x32_bf16 v[66:69], v[210:213], v[242:245], v[66:69]
	s_setprio 0
	s_barrier
	s_add_i32 s26, s95, s43
	v_lshl_add_u64 v[246:247], s[64:65], 0, v[136:137]
	s_mov_b32 m0, s26
	ds_read_b128 v[214:217], v201 offset:16384
	ds_read_b128 v[218:221], v201 offset:17408
	ds_read_b128 v[222:225], v201 offset:18432
	ds_read_b128 v[226:229], v201 offset:19456
	ds_read_b128 v[230:233], v201 offset:20480
	ds_read_b128 v[234:237], v201 offset:21504
	ds_read_b128 v[238:241], v201 offset:22528
	ds_read_b128 v[242:245], v201 offset:23552
	global_load_lds_dwordx4 v[246:247], off
	s_add_i32 m0, s26, 0x2000
	s_add_u32 s26, s64, 0x40000
	v_lshl_add_u64 v[248:249], s[64:65], 0, v[140:141]
	s_addc_u32 s27, s65, 0
	s_add_i32 s30, s30, s43
	global_load_lds_dwordx4 v[248:249], off
	v_lshl_add_u64 v[250:251], s[26:27], 0, v[136:137]
	s_mov_b32 m0, s30
	v_lshl_add_u64 v[252:253], s[68:69], 0, v[138:139]
	global_load_lds_dwordx4 v[250:251], off
	v_lshl_add_u64 v[250:251], s[26:27], 0, v[140:141]
	s_add_i32 m0, s30, 0x2000
	s_nop 0
	global_load_lds_dwordx4 v[250:251], off
	v_lshl_add_u64 v[250:251], s[68:69], 0, v[134:135]
	s_mov_b32 m0, s85
	s_nop 0
	global_load_lds_dwordx4 v[250:251], off
	s_mov_b32 m0, s76
	s_nop 0
	global_load_lds_dwordx4 v[252:253], off
	s_waitcnt vmcnt(8)
	s_waitcnt lgkmcnt(0)
	s_barrier
	s_setprio 1
	s_waitcnt lgkmcnt(0)
	v_mfma_f32_16x16x32_bf16 v[62:65], v[164:167], v[214:217], v[62:65]
	v_mfma_f32_16x16x32_bf16 v[58:61], v[172:175], v[214:217], v[58:61]
	v_mfma_f32_16x16x32_bf16 v[46:49], v[164:167], v[222:225], v[46:49]
	v_mfma_f32_16x16x32_bf16 v[42:45], v[172:175], v[222:225], v[42:45]
	v_mfma_f32_16x16x32_bf16 v[30:33], v[164:167], v[230:233], v[30:33]
	v_mfma_f32_16x16x32_bf16 v[26:29], v[172:175], v[230:233], v[26:29]
	v_mfma_f32_16x16x32_bf16 v[14:17], v[164:167], v[238:241], v[14:17]
	v_mfma_f32_16x16x32_bf16 v[10:13], v[172:175], v[238:241], v[10:13]
	v_mfma_f32_16x16x32_bf16 v[62:65], v[168:171], v[218:221], v[62:65]
	v_mfma_f32_16x16x32_bf16 v[58:61], v[176:179], v[218:221], v[58:61]
	v_mfma_f32_16x16x32_bf16 v[46:49], v[168:171], v[226:229], v[46:49]
	v_mfma_f32_16x16x32_bf16 v[42:45], v[176:179], v[226:229], v[42:45]
	v_mfma_f32_16x16x32_bf16 v[30:33], v[168:171], v[234:237], v[30:33]
	v_mfma_f32_16x16x32_bf16 v[26:29], v[176:179], v[234:237], v[26:29]
	v_mfma_f32_16x16x32_bf16 v[14:17], v[168:171], v[242:245], v[14:17]
	v_mfma_f32_16x16x32_bf16 v[10:13], v[176:179], v[242:245], v[10:13]
	s_setprio 0
	s_setprio 1
	v_mfma_f32_16x16x32_bf16 v[54:57], v[180:183], v[214:217], v[54:57]
	v_mfma_f32_16x16x32_bf16 v[50:53], v[206:209], v[214:217], v[50:53]
	v_mfma_f32_16x16x32_bf16 v[38:41], v[180:183], v[222:225], v[38:41]
	v_mfma_f32_16x16x32_bf16 v[34:37], v[206:209], v[222:225], v[34:37]
	v_mfma_f32_16x16x32_bf16 v[22:25], v[180:183], v[230:233], v[22:25]
	v_mfma_f32_16x16x32_bf16 v[18:21], v[206:209], v[230:233], v[18:21]
	v_mfma_f32_16x16x32_bf16 v[6:9], v[180:183], v[238:241], v[6:9]
	v_mfma_f32_16x16x32_bf16 v[2:5], v[206:209], v[238:241], v[2:5]
	v_mfma_f32_16x16x32_bf16 v[54:57], v[202:205], v[218:221], v[54:57]
	v_mfma_f32_16x16x32_bf16 v[50:53], v[210:213], v[218:221], v[50:53]
	v_mfma_f32_16x16x32_bf16 v[38:41], v[202:205], v[226:229], v[38:41]
	v_mfma_f32_16x16x32_bf16 v[34:37], v[210:213], v[226:229], v[34:37]
	v_mfma_f32_16x16x32_bf16 v[22:25], v[202:205], v[234:237], v[22:25]
	v_mfma_f32_16x16x32_bf16 v[18:21], v[210:213], v[234:237], v[18:21]
	v_mfma_f32_16x16x32_bf16 v[6:9], v[202:205], v[242:245], v[6:9]
	v_mfma_f32_16x16x32_bf16 v[2:5], v[210:213], v[242:245], v[2:5]
	s_setprio 0
	s_barrier
; #define PG8_STAGE(bufoff, gbase, voff) do { _Pragma("unroll") for (int _i = 0; _i < 2; ++_i) \
;         __builtin_amdgcn_global_load_lds((const unsigned*)((const char*)(gbase) + (voff)[_i]), (LAS unsigned*)(lds + (bufoff) + ldsw + _i * 8192), 16, 0, 0); } while (0)
; #define PG8_LDA(dst, b, h) do { _Pragma("unroll") for (int m = 0; m < 4; ++m) _Pragma("unroll") for (int k = 0; k < 2; ++k) dst[m][k] = *(const LAS bf16x8*)(lds + PG8_SA(b, h) + aoff + m * 2048 + k * 1024); } while (0)
; #define PG8_LDB(dst, b, h) do { _Pragma("unroll") for (int n = 0; n < 2; ++n) _Pragma("unroll") for (int k = 0; k < 2; ++k) dst[n][k] = *(const LAS bf16x8*)(lds + PG8_SB(b, h) + boff + n * 2048 + k * 1024); } while (0)
; #define PG8_MMA(ai, bj, At, Bt) do { __builtin_amdgcn_s_setprio(1); _Pragma("unroll") for (int m = 0; m < 4; ++m) _Pragma("unroll") for (int n = 0; n < 2; ++n) _Pragma("unroll") for (int k = 0; k < 2; ++k) \
;         acc[ai][bj][m][n] = __builtin_amdgcn_mfma_f32_16x16x32_bf16(Bt[n][k], At[m][k], acc[ai][bj][m][n], 0, 0, 0); __builtin_amdgcn_s_setprio(0); } while (0)
; #define PG8_WAIT_V(n) asm volatile("s_waitcnt vmcnt(" #n ")" ::: "memory")
; #define PG8_WAIT_L(n) asm volatile("s_waitcnt lgkmcnt(" #n ")" ::: "memory")
; #define PG8_BAR __builtin_amdgcn_s_barrier()
; #define PG8_SCHED __builtin_amdgcn_sched_barrier(0)
; template <class Epi, class Sched>
; __device__ __forceinline__ void gemm_phase(LAS unsigned char* lds, const Gemm g, const Sched& S, const Epi& E, const int tid) {
;     ...
;             PG8_LDB(B0, 1, 0); PG8_LDB(B1, 1, 1); PG8_SCHED; PG8_LDA(At, 1, 0); PG8_STAGE(PG8_SA(0, 1), a2 + hstep, voffA);
;             PG8_WAIT_V(8); PG8_WAIT_L(0); PG8_BAR; PG8_MMA(0, 0, At, B0); PG8_MMA(0, 1, At, B1); PG8_BAR; PG8_SCHED;
	s_add_i32 s30, 0, 0x18000
	v_add_u32_e32 v0, s30, v198
	s_add_i32 s95, 0, 0x1c000
	ds_read_b128 v[164:167], v0
	ds_read_b128 v[168:171], v0 offset:1024
	ds_read_b128 v[172:175], v0 offset:2048
	ds_read_b128 v[176:179], v0 offset:3072
	v_add_u32_e32 v0, s95, v198
	ds_read_b128 v[180:183], v0
	ds_read_b128 v[202:205], v0 offset:1024
	ds_read_b128 v[206:209], v0 offset:2048
	ds_read_b128 v[210:213], v0 offset:3072
	s_add_u32 s26, s68, 0x40000
	s_addc_u32 s27, s69, 0
	s_mov_b32 m0, s81
	v_lshl_add_u64 v[192:193], s[26:27], 0, v[134:135]
	ds_read_b128 v[214:217], v201 offset:32768
	ds_read_b128 v[218:221], v201 offset:33792
	ds_read_b128 v[222:225], v201 offset:34816
	ds_read_b128 v[226:229], v201 offset:35840
	ds_read_b128 v[230:233], v201 offset:36864
	ds_read_b128 v[234:237], v201 offset:37888
	ds_read_b128 v[238:241], v201 offset:38912
	ds_read_b128 v[242:245], v201 offset:39936
	global_load_lds_dwordx4 v[192:193], off
	v_lshl_add_u64 v[192:193], s[26:27], 0, v[138:139]
	s_mov_b32 m0, s84
	s_nop 0
	global_load_lds_dwordx4 v[192:193], off
	s_waitcnt vmcnt(8)
	s_waitcnt lgkmcnt(0)
	s_barrier
	s_setprio 1
	s_waitcnt lgkmcnt(0)
	v_mfma_f32_16x16x32_bf16 v[126:129], v[164:167], v[214:217], v[126:129]
	v_mfma_f32_16x16x32_bf16 v[122:125], v[172:175], v[214:217], v[122:125]
	v_mfma_f32_16x16x32_bf16 v[110:113], v[164:167], v[222:225], v[110:113]
	v_mfma_f32_16x16x32_bf16 v[106:109], v[172:175], v[222:225], v[106:109]
	v_mfma_f32_16x16x32_bf16 v[94:97], v[164:167], v[230:233], v[94:97]
	v_mfma_f32_16x16x32_bf16 v[90:93], v[172:175], v[230:233], v[90:93]
	v_mfma_f32_16x16x32_bf16 v[78:81], v[164:167], v[238:241], v[78:81]
	v_mfma_f32_16x16x32_bf16 v[74:77], v[172:175], v[238:241], v[74:77]
	v_mfma_f32_16x16x32_bf16 v[126:129], v[168:171], v[218:221], v[126:129]
	v_mfma_f32_16x16x32_bf16 v[122:125], v[176:179], v[218:221], v[122:125]
	v_mfma_f32_16x16x32_bf16 v[110:113], v[168:171], v[226:229], v[110:113]
	v_mfma_f32_16x16x32_bf16 v[106:109], v[176:179], v[226:229], v[106:109]
	v_mfma_f32_16x16x32_bf16 v[94:97], v[168:171], v[234:237], v[94:97]
	v_mfma_f32_16x16x32_bf16 v[90:93], v[176:179], v[234:237], v[90:93]
	v_mfma_f32_16x16x32_bf16 v[78:81], v[168:171], v[242:245], v[78:81]
	v_mfma_f32_16x16x32_bf16 v[74:77], v[176:179], v[242:245], v[74:77]
	s_setprio 0
	s_setprio 1
	v_mfma_f32_16x16x32_bf16 v[118:121], v[180:183], v[214:217], v[118:121]
	v_mfma_f32_16x16x32_bf16 v[114:117], v[206:209], v[214:217], v[114:117]
	v_mfma_f32_16x16x32_bf16 v[102:105], v[180:183], v[222:225], v[102:105]
	v_mfma_f32_16x16x32_bf16 v[98:101], v[206:209], v[222:225], v[98:101]
	v_mfma_f32_16x16x32_bf16 v[86:89], v[180:183], v[230:233], v[86:89]
	v_mfma_f32_16x16x32_bf16 v[82:85], v[206:209], v[230:233], v[82:85]
	v_mfma_f32_16x16x32_bf16 v[70:73], v[180:183], v[238:241], v[70:73]
	v_mfma_f32_16x16x32_bf16 v[66:69], v[206:209], v[238:241], v[66:69]
	v_mfma_f32_16x16x32_bf16 v[118:121], v[202:205], v[218:221], v[118:121]
	v_mfma_f32_16x16x32_bf16 v[114:117], v[210:213], v[218:221], v[114:117]
	v_mfma_f32_16x16x32_bf16 v[102:105], v[202:205], v[226:229], v[102:105]
	v_mfma_f32_16x16x32_bf16 v[98:101], v[210:213], v[226:229], v[98:101]
	v_mfma_f32_16x16x32_bf16 v[86:89], v[202:205], v[234:237], v[86:89]
	v_mfma_f32_16x16x32_bf16 v[82:85], v[210:213], v[234:237], v[82:85]
	v_mfma_f32_16x16x32_bf16 v[70:73], v[202:205], v[242:245], v[70:73]
	v_mfma_f32_16x16x32_bf16 v[66:69], v[210:213], v[242:245], v[66:69]
	s_setprio 0
	s_barrier
; #define PG8_STAGE(bufoff, gbase, voff) do { _Pragma("unroll") for (int _i = 0; _i < 2; ++_i) \
;         __builtin_amdgcn_global_load_lds((const unsigned*)((const char*)(gbase) + (voff)[_i]), (LAS unsigned*)(lds + (bufoff) + ldsw + _i * 8192), 16, 0, 0); } while (0)
; #define PG8_LDA(dst, b, h) do { _Pragma("unroll") for (int m = 0; m < 4; ++m) _Pragma("unroll") for (int k = 0; k < 2; ++k) dst[m][k] = *(const LAS bf16x8*)(lds + PG8_SA(b, h) + aoff + m * 2048 + k * 1024); } while (0)
; #define PG8_MMA(ai, bj, At, Bt) do { __builtin_amdgcn_s_setprio(1); _Pragma("unroll") for (int m = 0; m < 4; ++m) _Pragma("unroll") for (int n = 0; n < 2; ++n) _Pragma("unroll") for (int k = 0; k < 2; ++k) \
;         acc[ai][bj][m][n] = __builtin_amdgcn_mfma_f32_16x16x32_bf16(Bt[n][k], At[m][k], acc[ai][bj][m][n], 0, 0, 0); __builtin_amdgcn_s_setprio(0); } while (0)
; #define PG8_WAIT_V(n) asm volatile("s_waitcnt vmcnt(" #n ")" ::: "memory")
; #define PG8_WAIT_L(n) asm volatile("s_waitcnt lgkmcnt(" #n ")" ::: "memory")
; #define PG8_BAR __builtin_amdgcn_s_barrier()
; #define PG8_SCHED __builtin_amdgcn_sched_barrier(0)
; template <class Epi, class Sched>
; __device__ __forceinline__ void gemm_phase(LAS unsigned char* lds, const Gemm g, const Sched& S, const Epi& E, const int tid) {
;     ...
;         for (int t = 0; t < nt; t += 2) {
;             if constexpr (Epi::CHAIN) { if (t == 8 || t == 12) { E.mid(acc, cur, t == 8 ? 0 : 1, wr, wc, fr, fq); PG8_SCHED; } }
;             const bool last = (t == nt - 2);
;             const char* a1 = cA + (size_t)(t + 1) * kstep;
;             const char* a2 = last ? nA : cA + (size_t)(t + 2) * kstep; const char* b2 = last ? nB : cB + (size_t)(t + 2) * kstep;
;             const char* a3 = a2 + kstep; const char* b3 = b2 + kstep;
;     ...
;             PG8_LDA(At, 1, 1); PG8_STAGE(PG8_SB(1, 0), b3, voffB); PG8_STAGE(PG8_SB(1, 1), b3 + hstep, voffB); PG8_STAGE(PG8_SA(1, 0), a3, voffA);
;             PG8_WAIT_V(8); PG8_WAIT_L(0); PG8_BAR; PG8_MMA(1, 0, At, B0); PG8_MMA(1, 1, At, B1); PG8_BAR; PG8_SCHED;
;         }
	s_add_i32 s26, s30, s43
	v_lshl_add_u64 v[192:193], v[246:247], 0, s[34:35]
	s_mov_b32 m0, s26
	ds_read_b128 v[214:217], v201 offset:49152
	ds_read_b128 v[218:221], v201 offset:50176
	ds_read_b128 v[222:225], v201 offset:51200
	ds_read_b128 v[226:229], v201 offset:52224
	ds_read_b128 v[230:233], v201 offset:53248
	ds_read_b128 v[234:237], v201 offset:54272
	ds_read_b128 v[238:241], v201 offset:55296
	ds_read_b128 v[242:245], v201 offset:56320
	global_load_lds_dwordx4 v[192:193], off
	s_add_i32 m0, s26, 0x2000
	s_add_u32 s26, s64, 0x40080
	v_lshl_add_u64 v[192:193], v[248:249], 0, s[34:35]
	s_addc_u32 s27, s65, 0
	s_add_i32 s30, s95, s43
	global_load_lds_dwordx4 v[192:193], off
	v_lshl_add_u64 v[192:193], s[26:27], 0, v[136:137]
	s_mov_b32 m0, s30
	s_nop 0
	global_load_lds_dwordx4 v[192:193], off
	v_lshl_add_u64 v[192:193], s[26:27], 0, v[140:141]
	s_add_i32 m0, s30, 0x2000
	s_nop 0
	global_load_lds_dwordx4 v[192:193], off
	v_lshl_add_u64 v[192:193], v[250:251], 0, s[34:35]
	s_mov_b32 m0, s88
	s_nop 0
	global_load_lds_dwordx4 v[192:193], off
	v_lshl_add_u64 v[192:193], v[252:253], 0, s[34:35]
	s_mov_b32 m0, s89
	s_nop 0
	global_load_lds_dwordx4 v[192:193], off
	s_waitcnt vmcnt(8)
	s_waitcnt lgkmcnt(0)
	s_barrier
	s_setprio 1
	s_waitcnt lgkmcnt(0)
	v_mfma_f32_16x16x32_bf16 v[62:65], v[164:167], v[214:217], v[62:65]
	v_mfma_f32_16x16x32_bf16 v[58:61], v[172:175], v[214:217], v[58:61]
	v_mfma_f32_16x16x32_bf16 v[46:49], v[164:167], v[222:225], v[46:49]
	v_mfma_f32_16x16x32_bf16 v[42:45], v[172:175], v[222:225], v[42:45]
	v_mfma_f32_16x16x32_bf16 v[30:33], v[164:167], v[230:233], v[30:33]
	v_mfma_f32_16x16x32_bf16 v[26:29], v[172:175], v[230:233], v[26:29]
	v_mfma_f32_16x16x32_bf16 v[14:17], v[164:167], v[238:241], v[14:17]
	v_mfma_f32_16x16x32_bf16 v[10:13], v[172:175], v[238:241], v[10:13]
	v_mfma_f32_16x16x32_bf16 v[62:65], v[168:171], v[218:221], v[62:65]
	v_mfma_f32_16x16x32_bf16 v[58:61], v[176:179], v[218:221], v[58:61]
	v_mfma_f32_16x16x32_bf16 v[46:49], v[168:171], v[226:229], v[46:49]
	v_mfma_f32_16x16x32_bf16 v[42:45], v[176:179], v[226:229], v[42:45]
	v_mfma_f32_16x16x32_bf16 v[30:33], v[168:171], v[234:237], v[30:33]
	v_mfma_f32_16x16x32_bf16 v[26:29], v[176:179], v[234:237], v[26:29]
	v_mfma_f32_16x16x32_bf16 v[14:17], v[168:171], v[242:245], v[14:17]
	v_mfma_f32_16x16x32_bf16 v[10:13], v[176:179], v[242:245], v[10:13]
	s_setprio 0
	s_setprio 1
	v_mfma_f32_16x16x32_bf16 v[54:57], v[180:183], v[214:217], v[54:57]
	v_mfma_f32_16x16x32_bf16 v[50:53], v[206:209], v[214:217], v[50:53]
	v_mfma_f32_16x16x32_bf16 v[38:41], v[180:183], v[222:225], v[38:41]
	v_mfma_f32_16x16x32_bf16 v[34:37], v[206:209], v[222:225], v[34:37]
	v_mfma_f32_16x16x32_bf16 v[22:25], v[180:183], v[230:233], v[22:25]
	v_mfma_f32_16x16x32_bf16 v[18:21], v[206:209], v[230:233], v[18:21]
	v_mfma_f32_16x16x32_bf16 v[6:9], v[180:183], v[238:241], v[6:9]
	v_mfma_f32_16x16x32_bf16 v[2:5], v[206:209], v[238:241], v[2:5]
	v_mfma_f32_16x16x32_bf16 v[54:57], v[202:205], v[218:221], v[54:57]
	v_mfma_f32_16x16x32_bf16 v[50:53], v[210:213], v[218:221], v[50:53]
	v_mfma_f32_16x16x32_bf16 v[38:41], v[202:205], v[226:229], v[38:41]
	v_mfma_f32_16x16x32_bf16 v[34:37], v[210:213], v[226:229], v[34:37]
	v_mfma_f32_16x16x32_bf16 v[22:25], v[202:205], v[234:237], v[22:25]
	v_mfma_f32_16x16x32_bf16 v[18:21], v[210:213], v[234:237], v[18:21]
	v_mfma_f32_16x16x32_bf16 v[6:9], v[202:205], v[242:245], v[6:9]
	v_mfma_f32_16x16x32_bf16 v[2:5], v[210:213], v[242:245], v[2:5]
	s_setprio 0
	s_add_i32 s72, s72, 2
	s_add_u32 s62, s62, 0x100
	s_addc_u32 s63, s63, 0
	s_add_u32 vcc_lo, vcc_lo, 0x100
	s_addc_u32 vcc_hi, vcc_hi, 0
	s_add_u32 s26, s62, 0xfffc0080
	s_addc_u32 s27, s63, -1
	s_add_i32 s95, 0, 0x10000
	s_cmp_eq_u32 s72, 12
	s_cselect_b32 s69, s28, s27
	s_cselect_b32 s68, s57, s26
	s_cselect_b32 s65, s55, vcc_hi
	s_cselect_b32 s64, s67, vcc_lo
	s_add_i32 s30, 0, 0x14000
	s_cmp_gt_u32 s72, 13
	s_barrier
	s_cbranch_scc0 .LBB0_239
	s_and_b64 vcc, exec, s[48:49]
	s_cbranch_vccz .LBB0_242
	s_barrier

; #define PG8_STAGE(bufoff, gbase, voff) do { _Pragma("unroll") for (int _i = 0; _i < 2; ++_i) \
;         __builtin_amdgcn_global_load_lds((const unsigned*)((const char*)(gbase) + (voff)[_i]), (LAS unsigned*)(lds + (bufoff) + ldsw + _i * 8192), 16, 0, 0); } while (0)
; #define PG8_LDA(dst, b, h) do { _Pragma("unroll") for (int m = 0; m < 4; ++m) _Pragma("unroll") for (int k = 0; k < 2; ++k) dst[m][k] = *(const LAS bf16x8*)(lds + PG8_SA(b, h) + aoff + m * 2048 + k * 1024); } while (0)
; #define PG8_LDB(dst, b, h) do { _Pragma("unroll") for (int n = 0; n < 2; ++n) _Pragma("unroll") for (int k = 0; k < 2; ++k) dst[n][k] = *(const LAS bf16x8*)(lds + PG8_SB(b, h) + boff + n * 2048 + k * 1024); } while (0)
; #define PG8_WAIT_V(n) asm volatile("s_waitcnt vmcnt(" #n ")" ::: "memory")
; #define PG8_WAIT_L(n) asm volatile("s_waitcnt lgkmcnt(" #n ")" ::: "memory")
; template <class Epi, class Sched>
; __device__ __forceinline__ void gemm_phase(LAS unsigned char* lds, const Gemm g, const Sched& S, const Epi& E, const int tid) {
;     ...
;         const char* nA = has_next ? (const char*)g.A + (size_t)nxt.pm * tstep + (size_t)nxt.koff * 2 : cA; const char* nB = has_next ? (const char*)g.Bt + (size_t)nxt.pn * tstep + (size_t)nxt.koff * 2 : cB;
;         const int nt = cur.nt;
;         for (int t = 0; t < nt; t += 2) {
;             if constexpr (Epi::CHAIN) { if (t == 8 || t == 12) { E.mid(acc, cur, t == 8 ? 0 : 1, wr, wc, fr, fq); PG8_SCHED; } }
;             const bool last = (t == nt - 2);
;             const char* a1 = cA + (size_t)(t + 1) * kstep;
;             const char* a2 = last ? nA : cA + (size_t)(t + 2) * kstep; const char* b2 = last ? nB : cB + (size_t)(t + 2) * kstep;
;             const char* a3 = a2 + kstep; const char* b3 = b2 + kstep;
;             PG8_LDB(B0, 0, 0); PG8_LDB(B1, 0, 1); PG8_SCHED; PG8_LDA(At, 0, 0); PG8_STAGE(PG8_SA(1, 1), a1 + hstep, voffA);
;             PG8_WAIT_V(8); PG8_WAIT_L(0); PG8_BAR; PG8_MMA(0, 0, At, B0); PG8_MMA(0, 1, At, B1); PG8_BAR; PG8_SCHED;
;     ...
;         if (!(Epi::CHAIN && nxt.seg != 0))
; #pragma unroll
;         for (int a = 0; a < 2; ++a)
; #pragma unroll
;             for (int b = 0; b < 2; ++b)
; #pragma unroll
;                 for (int m = 0; m < 4; ++m)
; #pragma unroll
;                     for (int n = 0; n < 2; ++n) acc[a][b][m][n] = (f32x4){0.f, 0.f, 0.f, 0.f};
;         cur = nxt; cA = nA; cB = nB; ++ui;
.LBB0_417:
	s_add_u32 s69, s52, 0x100
	v_mov_b32_e32 v2, 0
	s_addc_u32 s70, s53, 0
	s_mov_b32 s71, -2
	s_waitcnt lgkmcnt(0)
	v_mov_b32_e32 v3, v2
	v_mov_b32_e32 v4, v2
	v_mov_b32_e32 v5, v2
	v_mov_b32_e32 v6, v2
	v_mov_b32_e32 v7, v2
	v_mov_b32_e32 v8, v2
	v_mov_b32_e32 v9, v2
	v_mov_b32_e32 v18, v2
	v_mov_b32_e32 v19, v2
	v_mov_b32_e32 v20, v2
	v_mov_b32_e32 v21, v2
	v_mov_b32_e32 v22, v2
	v_mov_b32_e32 v23, v2
	v_mov_b32_e32 v24, v2
	v_mov_b32_e32 v25, v2
	v_mov_b32_e32 v34, v2
	v_mov_b32_e32 v35, v2
	v_mov_b32_e32 v36, v2
	v_mov_b32_e32 v37, v2
	v_mov_b32_e32 v38, v2
	v_mov_b32_e32 v39, v2
	v_mov_b32_e32 v40, v2
	v_mov_b32_e32 v41, v2
	v_mov_b32_e32 v50, v2
	v_mov_b32_e32 v51, v2
	v_mov_b32_e32 v52, v2
	v_mov_b32_e32 v53, v2
	v_mov_b32_e32 v54, v2
	v_mov_b32_e32 v55, v2
	v_mov_b32_e32 v56, v2
	v_mov_b32_e32 v57, v2
	v_mov_b32_e32 v10, v2
	v_mov_b32_e32 v11, v2
	v_mov_b32_e32 v12, v2
	v_mov_b32_e32 v13, v2
	v_mov_b32_e32 v14, v2
	v_mov_b32_e32 v15, v2
	v_mov_b32_e32 v16, v2
	v_mov_b32_e32 v17, v2
	v_mov_b32_e32 v26, v2
	v_mov_b32_e32 v27, v2
	v_mov_b32_e32 v28, v2
	v_mov_b32_e32 v29, v2
	v_mov_b32_e32 v30, v2
	v_mov_b32_e32 v31, v2
	v_mov_b32_e32 v32, v2
	v_mov_b32_e32 v33, v2
	v_mov_b32_e32 v42, v2
	v_mov_b32_e32 v43, v2
	v_mov_b32_e32 v44, v2
	v_mov_b32_e32 v45, v2
	v_mov_b32_e32 v46, v2
	v_mov_b32_e32 v47, v2
	v_mov_b32_e32 v48, v2
	v_mov_b32_e32 v49, v2
	v_mov_b32_e32 v58, v2
	v_mov_b32_e32 v59, v2
	v_mov_b32_e32 v60, v2
	v_mov_b32_e32 v61, v2
	v_mov_b32_e32 v62, v2
	v_mov_b32_e32 v63, v2
	v_mov_b32_e32 v64, v2
	v_mov_b32_e32 v65, v2
	v_mov_b32_e32 v66, v2
	v_mov_b32_e32 v67, v2
	v_mov_b32_e32 v68, v2
	v_mov_b32_e32 v69, v2
	v_mov_b32_e32 v70, v2
	v_mov_b32_e32 v71, v2
	v_mov_b32_e32 v72, v2
	v_mov_b32_e32 v73, v2
	v_mov_b32_e32 v82, v2
	v_mov_b32_e32 v83, v2
	v_mov_b32_e32 v84, v2
	v_mov_b32_e32 v85, v2
	s_waitcnt vmcnt(0)
	v_mov_b32_e32 v86, v2
	v_mov_b32_e32 v87, v2
	v_mov_b32_e32 v88, v2
	v_mov_b32_e32 v89, v2
	v_mov_b32_e32 v98, v2
	v_mov_b32_e32 v99, v2
	v_mov_b32_e32 v100, v2
	v_mov_b32_e32 v101, v2
	v_mov_b32_e32 v102, v2
	v_mov_b32_e32 v103, v2
	v_mov_b32_e32 v104, v2
	v_mov_b32_e32 v105, v2
	v_mov_b32_e32 v114, v2
	v_mov_b32_e32 v115, v2
	v_mov_b32_e32 v116, v2
	v_mov_b32_e32 v117, v2
	v_mov_b32_e32 v118, v2
	v_mov_b32_e32 v119, v2
	v_mov_b32_e32 v120, v2
	v_mov_b32_e32 v121, v2
	v_mov_b32_e32 v74, v2
	v_mov_b32_e32 v75, v2
	v_mov_b32_e32 v76, v2
	v_mov_b32_e32 v77, v2
	v_mov_b32_e32 v78, v2
	v_mov_b32_e32 v79, v2
	v_mov_b32_e32 v80, v2
	v_mov_b32_e32 v81, v2
	v_mov_b32_e32 v90, v2
	v_mov_b32_e32 v91, v2
	v_mov_b32_e32 v92, v2
	v_mov_b32_e32 v93, v2
	v_mov_b32_e32 v94, v2
	v_mov_b32_e32 v95, v2
	v_mov_b32_e32 v96, v2
	v_mov_b32_e32 v97, v2
	v_mov_b32_e32 v106, v2
	v_mov_b32_e32 v107, v2
	v_mov_b32_e32 v108, v2
	v_mov_b32_e32 v109, v2
	v_mov_b32_e32 v110, v2
	v_mov_b32_e32 v111, v2
	v_mov_b32_e32 v112, v2
	v_mov_b32_e32 v113, v2
	v_mov_b32_e32 v122, v2
	v_mov_b32_e32 v123, v2
	v_mov_b32_e32 v124, v2
	v_mov_b32_e32 v125, v2
	v_mov_b32_e32 v126, v2
	v_mov_b32_e32 v127, v2
	v_mov_b32_e32 v128, v2
	v_mov_b32_e32 v129, v2
	s_add_u32 s52, s50, 0x100
	s_addc_u32 s53, s51, 0
	s_add_i32 s26, 0, 0x10000
	s_cmp_eq_u32 s71, 40
	s_cselect_b32 s57, s9, s53
	s_cselect_b32 s56, s8, s52
	s_cselect_b32 s55, s49, s70
	s_cselect_b32 s54, s48, s69
	s_add_i32 s30, 0, 0x14000
.LBB0_418:
	v_add_u32_e32 v140, s26, v143
	ds_read_b128 v[136:139], v140
	ds_read_b128 v[156:159], v140 offset:1024
	ds_read_b128 v[160:163], v140 offset:2048
	ds_read_b128 v[164:167], v140 offset:3072
	v_add_u32_e32 v140, s30, v143
	ds_read_b128 v[168:171], v140
	ds_read_b128 v[172:175], v140 offset:1024
	ds_read_b128 v[176:179], v140 offset:2048
	ds_read_b128 v[180:183], v140 offset:3072
	v_lshl_add_u64 v[140:141], s[50:51], 0, v[132:133]
	s_add_i32 m0, s44, 0xc000
	ds_read_b128 v[198:201], v145
	ds_read_b128 v[202:205], v145 offset:1024
	ds_read_b128 v[206:209], v145 offset:2048
	ds_read_b128 v[210:213], v145 offset:3072
	ds_read_b128 v[214:217], v145 offset:4096
	ds_read_b128 v[218:221], v145 offset:5120
	ds_read_b128 v[222:225], v145 offset:6144
	ds_read_b128 v[226:229], v145 offset:7168
	global_load_lds_dwordx4 v[140:141], off
	v_lshl_add_u64 v[140:141], s[50:51], 0, v[134:135]
	s_add_i32 m0, s44, 0xe000
	s_nop 0
	global_load_lds_dwordx4 v[140:141], off
	s_waitcnt vmcnt(8)
	s_waitcnt lgkmcnt(0)
	s_barrier
	s_setprio 1
	s_waitcnt lgkmcnt(0)
	v_mfma_f32_16x16x32_bf16 v[126:129], v[136:139], v[198:201], v[126:129]
	v_mfma_f32_16x16x32_bf16 v[122:125], v[160:163], v[198:201], v[122:125]
	v_mfma_f32_16x16x32_bf16 v[110:113], v[136:139], v[206:209], v[110:113]
	v_mfma_f32_16x16x32_bf16 v[106:109], v[160:163], v[206:209], v[106:109]
	v_mfma_f32_16x16x32_bf16 v[94:97], v[136:139], v[214:217], v[94:97]
	v_mfma_f32_16x16x32_bf16 v[90:93], v[160:163], v[214:217], v[90:93]
	v_mfma_f32_16x16x32_bf16 v[78:81], v[136:139], v[222:225], v[78:81]
	v_mfma_f32_16x16x32_bf16 v[74:77], v[160:163], v[222:225], v[74:77]
	v_mfma_f32_16x16x32_bf16 v[126:129], v[156:159], v[202:205], v[126:129]
	v_mfma_f32_16x16x32_bf16 v[122:125], v[164:167], v[202:205], v[122:125]
	v_mfma_f32_16x16x32_bf16 v[110:113], v[156:159], v[210:213], v[110:113]
	v_mfma_f32_16x16x32_bf16 v[106:109], v[164:167], v[210:213], v[106:109]
	v_mfma_f32_16x16x32_bf16 v[94:97], v[156:159], v[218:221], v[94:97]
	v_mfma_f32_16x16x32_bf16 v[90:93], v[164:167], v[218:221], v[90:93]
	v_mfma_f32_16x16x32_bf16 v[78:81], v[156:159], v[226:229], v[78:81]
	v_mfma_f32_16x16x32_bf16 v[74:77], v[164:167], v[226:229], v[74:77]
	s_setprio 0
	s_setprio 1
	v_mfma_f32_16x16x32_bf16 v[118:121], v[168:171], v[198:201], v[118:121]
	v_mfma_f32_16x16x32_bf16 v[114:117], v[176:179], v[198:201], v[114:117]
	v_mfma_f32_16x16x32_bf16 v[102:105], v[168:171], v[206:209], v[102:105]
	v_mfma_f32_16x16x32_bf16 v[98:101], v[176:179], v[206:209], v[98:101]
	v_mfma_f32_16x16x32_bf16 v[86:89], v[168:171], v[214:217], v[86:89]
	v_mfma_f32_16x16x32_bf16 v[82:85], v[176:179], v[214:217], v[82:85]
	v_mfma_f32_16x16x32_bf16 v[70:73], v[168:171], v[222:225], v[70:73]
	v_mfma_f32_16x16x32_bf16 v[66:69], v[176:179], v[222:225], v[66:69]
	v_mfma_f32_16x16x32_bf16 v[118:121], v[172:175], v[202:205], v[118:121]
	v_mfma_f32_16x16x32_bf16 v[114:117], v[180:183], v[202:205], v[114:117]
	v_mfma_f32_16x16x32_bf16 v[102:105], v[172:175], v[210:213], v[102:105]
	v_mfma_f32_16x16x32_bf16 v[98:101], v[180:183], v[210:213], v[98:101]
	v_mfma_f32_16x16x32_bf16 v[86:89], v[172:175], v[218:221], v[86:89]
	v_mfma_f32_16x16x32_bf16 v[82:85], v[180:183], v[218:221], v[82:85]
	v_mfma_f32_16x16x32_bf16 v[70:73], v[172:175], v[226:229], v[70:73]
	v_mfma_f32_16x16x32_bf16 v[66:69], v[180:183], v[226:229], v[66:69]
	s_setprio 0
	s_barrier
; #define PG8_STAGE(bufoff, gbase, voff) do { _Pragma("unroll") for (int _i = 0; _i < 2; ++_i) \
;         __builtin_amdgcn_global_load_lds((const unsigned*)((const char*)(gbase) + (voff)[_i]), (LAS unsigned*)(lds + (bufoff) + ldsw + _i * 8192), 16, 0, 0); } while (0)
; #define PG8_LDA(dst, b, h) do { _Pragma("unroll") for (int m = 0; m < 4; ++m) _Pragma("unroll") for (int k = 0; k < 2; ++k) dst[m][k] = *(const LAS bf16x8*)(lds + PG8_SA(b, h) + aoff + m * 2048 + k * 1024); } while (0)
; #define PG8_LDB(dst, b, h) do { _Pragma("unroll") for (int n = 0; n < 2; ++n) _Pragma("unroll") for (int k = 0; k < 2; ++k) dst[n][k] = *(const LAS bf16x8*)(lds + PG8_SB(b, h) + boff + n * 2048 + k * 1024); } while (0)
; #define PG8_MMA(ai, bj, At, Bt) do { __builtin_amdgcn_s_setprio(1); _Pragma("unroll") for (int m = 0; m < 4; ++m) _Pragma("unroll") for (int n = 0; n < 2; ++n) _Pragma("unroll") for (int k = 0; k < 2; ++k) \
;         acc[ai][bj][m][n] = __builtin_amdgcn_mfma_f32_16x16x32_bf16(Bt[n][k], At[m][k], acc[ai][bj][m][n], 0, 0, 0); __builtin_amdgcn_s_setprio(0); } while (0)
; #define PG8_WAIT_V(n) asm volatile("s_waitcnt vmcnt(" #n ")" ::: "memory")
; #define PG8_WAIT_L(n) asm volatile("s_waitcnt lgkmcnt(" #n ")" ::: "memory")
; #define PG8_BAR __builtin_amdgcn_s_barrier()
; #define PG8_SCHED __builtin_amdgcn_sched_barrier(0)
; template <class Epi, class Sched>
; __device__ __forceinline__ void gemm_phase(LAS unsigned char* lds, const Gemm g, const Sched& S, const Epi& E, const int tid) {
;     ...
;             PG8_LDA(At, 0, 1); PG8_STAGE(PG8_SB(0, 0), b2, voffB); PG8_STAGE(PG8_SB(0, 1), b2 + hstep, voffB); PG8_STAGE(PG8_SA(0, 0), a2, voffA);
;             PG8_WAIT_V(8); PG8_WAIT_L(0); PG8_BAR; PG8_MMA(1, 0, At, B0); PG8_MMA(1, 1, At, B1); PG8_BAR; PG8_SCHED;
;             PG8_LDB(B0, 1, 0); PG8_LDB(B1, 1, 1); PG8_SCHED; PG8_LDA(At, 1, 0); PG8_STAGE(PG8_SA(0, 1), a2 + hstep, voffA);
;             PG8_WAIT_V(8); PG8_WAIT_L(0); PG8_BAR; PG8_MMA(0, 0, At, B0); PG8_MMA(0, 1, At, B1); PG8_BAR; PG8_SCHED;
	s_add_i32 s26, s26, s43
	v_lshl_add_u64 v[140:141], s[54:55], 0, v[0:1]
	s_mov_b32 m0, s26
	ds_read_b128 v[198:201], v145 offset:16384
	ds_read_b128 v[202:205], v145 offset:17408
	ds_read_b128 v[206:209], v145 offset:18432
	ds_read_b128 v[210:213], v145 offset:19456
	ds_read_b128 v[214:217], v145 offset:20480
	ds_read_b128 v[218:221], v145 offset:21504
	ds_read_b128 v[222:225], v145 offset:22528
	ds_read_b128 v[226:229], v145 offset:23552
	global_load_lds_dwordx4 v[140:141], off
	s_add_i32 m0, s26, 0x2000
	s_add_u32 s26, s54, 0xb0000
	v_lshl_add_u64 v[192:193], s[54:55], 0, v[130:131]
	s_addc_u32 s27, s55, 0
	s_add_i32 s30, s30, s43
	global_load_lds_dwordx4 v[192:193], off
	v_lshl_add_u64 v[230:231], s[26:27], 0, v[0:1]
	s_mov_b32 m0, s30
	v_lshl_add_u64 v[232:233], s[56:57], 0, v[130:131]
	global_load_lds_dwordx4 v[230:231], off
	v_lshl_add_u64 v[230:231], s[26:27], 0, v[130:131]
	s_add_i32 m0, s30, 0x2000
	s_nop 0
	global_load_lds_dwordx4 v[230:231], off
	v_lshl_add_u64 v[230:231], s[56:57], 0, v[0:1]
	s_mov_b32 m0, s44
	s_nop 0
	global_load_lds_dwordx4 v[230:231], off
	s_mov_b32 m0, s45
	s_nop 0
	global_load_lds_dwordx4 v[232:233], off
	s_waitcnt vmcnt(8)
	s_waitcnt lgkmcnt(0)
	s_barrier
	s_setprio 1
	s_waitcnt lgkmcnt(0)
	v_mfma_f32_16x16x32_bf16 v[62:65], v[136:139], v[198:201], v[62:65]
	v_mfma_f32_16x16x32_bf16 v[58:61], v[160:163], v[198:201], v[58:61]
	v_mfma_f32_16x16x32_bf16 v[46:49], v[136:139], v[206:209], v[46:49]
	v_mfma_f32_16x16x32_bf16 v[42:45], v[160:163], v[206:209], v[42:45]
	v_mfma_f32_16x16x32_bf16 v[30:33], v[136:139], v[214:217], v[30:33]
	v_mfma_f32_16x16x32_bf16 v[26:29], v[160:163], v[214:217], v[26:29]
	v_mfma_f32_16x16x32_bf16 v[14:17], v[136:139], v[222:225], v[14:17]
	v_mfma_f32_16x16x32_bf16 v[10:13], v[160:163], v[222:225], v[10:13]
	v_mfma_f32_16x16x32_bf16 v[62:65], v[156:159], v[202:205], v[62:65]
	v_mfma_f32_16x16x32_bf16 v[58:61], v[164:167], v[202:205], v[58:61]
	v_mfma_f32_16x16x32_bf16 v[46:49], v[156:159], v[210:213], v[46:49]
	v_mfma_f32_16x16x32_bf16 v[42:45], v[164:167], v[210:213], v[42:45]
	v_mfma_f32_16x16x32_bf16 v[30:33], v[156:159], v[218:221], v[30:33]
	v_mfma_f32_16x16x32_bf16 v[26:29], v[164:167], v[218:221], v[26:29]
	v_mfma_f32_16x16x32_bf16 v[14:17], v[156:159], v[226:229], v[14:17]
	v_mfma_f32_16x16x32_bf16 v[10:13], v[164:167], v[226:229], v[10:13]
	s_setprio 0
	s_setprio 1
	v_mfma_f32_16x16x32_bf16 v[54:57], v[168:171], v[198:201], v[54:57]
	v_mfma_f32_16x16x32_bf16 v[50:53], v[176:179], v[198:201], v[50:53]
	v_mfma_f32_16x16x32_bf16 v[38:41], v[168:171], v[206:209], v[38:41]
	v_mfma_f32_16x16x32_bf16 v[34:37], v[176:179], v[206:209], v[34:37]
	v_mfma_f32_16x16x32_bf16 v[22:25], v[168:171], v[214:217], v[22:25]
	v_mfma_f32_16x16x32_bf16 v[18:21], v[176:179], v[214:217], v[18:21]
	v_mfma_f32_16x16x32_bf16 v[6:9], v[168:171], v[222:225], v[6:9]
	v_mfma_f32_16x16x32_bf16 v[2:5], v[176:179], v[222:225], v[2:5]
	v_mfma_f32_16x16x32_bf16 v[54:57], v[172:175], v[202:205], v[54:57]
	v_mfma_f32_16x16x32_bf16 v[50:53], v[180:183], v[202:205], v[50:53]
	v_mfma_f32_16x16x32_bf16 v[38:41], v[172:175], v[210:213], v[38:41]
	v_mfma_f32_16x16x32_bf16 v[34:37], v[180:183], v[210:213], v[34:37]
	v_mfma_f32_16x16x32_bf16 v[22:25], v[172:175], v[218:221], v[22:25]
	v_mfma_f32_16x16x32_bf16 v[18:21], v[180:183], v[218:221], v[18:21]
	v_mfma_f32_16x16x32_bf16 v[6:9], v[172:175], v[226:229], v[6:9]
	v_mfma_f32_16x16x32_bf16 v[2:5], v[180:183], v[226:229], v[2:5]
	s_setprio 0
	s_barrier
	s_add_i32 s30, 0, 0x18000
	s_add_i32 s50, 0, 0x1c000
	v_add_u32_e32 v164, s30, v143
	v_add_u32_e32 v180, s50, v143
	ds_read_b128 v[136:139], v164
	ds_read_b128 v[156:159], v164 offset:1024
	ds_read_b128 v[160:163], v164 offset:2048
	ds_read_b128 v[164:167], v164 offset:3072
	ds_read_b128 v[168:171], v180
	ds_read_b128 v[172:175], v180 offset:1024
	ds_read_b128 v[176:179], v180 offset:2048
	ds_read_b128 v[180:183], v180 offset:3072
	s_add_u32 s26, s56, 0xb0000
	s_addc_u32 s27, s57, 0
	s_mov_b32 m0, s47
	v_lshl_add_u64 v[234:235], s[26:27], 0, v[0:1]
	ds_read_b128 v[198:201], v145 offset:32768
	ds_read_b128 v[202:205], v145 offset:33792
	ds_read_b128 v[206:209], v145 offset:34816
	ds_read_b128 v[210:213], v145 offset:35840
	ds_read_b128 v[214:217], v145 offset:36864
	ds_read_b128 v[218:221], v145 offset:37888
	ds_read_b128 v[222:225], v145 offset:38912
	ds_read_b128 v[226:229], v145 offset:39936
	global_load_lds_dwordx4 v[234:235], off
	v_lshl_add_u64 v[234:235], s[26:27], 0, v[130:131]
	s_mov_b32 m0, s58
	s_nop 0
	global_load_lds_dwordx4 v[234:235], off
	s_waitcnt vmcnt(8)
	s_waitcnt lgkmcnt(0)
	s_barrier
; #define PG8_STAGE(bufoff, gbase, voff) do { _Pragma("unroll") for (int _i = 0; _i < 2; ++_i) \
;         __builtin_amdgcn_global_load_lds((const unsigned*)((const char*)(gbase) + (voff)[_i]), (LAS unsigned*)(lds + (bufoff) + ldsw + _i * 8192), 16, 0, 0); } while (0)
; #define PG8_LDA(dst, b, h) do { _Pragma("unroll") for (int m = 0; m < 4; ++m) _Pragma("unroll") for (int k = 0; k < 2; ++k) dst[m][k] = *(const LAS bf16x8*)(lds + PG8_SA(b, h) + aoff + m * 2048 + k * 1024); } while (0)
; #define PG8_MMA(ai, bj, At, Bt) do { __builtin_amdgcn_s_setprio(1); _Pragma("unroll") for (int m = 0; m < 4; ++m) _Pragma("unroll") for (int n = 0; n < 2; ++n) _Pragma("unroll") for (int k = 0; k < 2; ++k) \
;         acc[ai][bj][m][n] = __builtin_amdgcn_mfma_f32_16x16x32_bf16(Bt[n][k], At[m][k], acc[ai][bj][m][n], 0, 0, 0); __builtin_amdgcn_s_setprio(0); } while (0)
; #define PG8_WAIT_V(n) asm volatile("s_waitcnt vmcnt(" #n ")" ::: "memory")
; #define PG8_WAIT_L(n) asm volatile("s_waitcnt lgkmcnt(" #n ")" ::: "memory")
; #define PG8_BAR __builtin_amdgcn_s_barrier()
; #define PG8_SCHED __builtin_amdgcn_sched_barrier(0)
; template <class Epi, class Sched>
; __device__ __forceinline__ void gemm_phase(LAS unsigned char* lds, const Gemm g, const Sched& S, const Epi& E, const int tid) {
;     ...
;         for (int t = 0; t < nt; t += 2) {
;             if constexpr (Epi::CHAIN) { if (t == 8 || t == 12) { E.mid(acc, cur, t == 8 ? 0 : 1, wr, wc, fr, fq); PG8_SCHED; } }
;             const bool last = (t == nt - 2);
;             const char* a1 = cA + (size_t)(t + 1) * kstep;
;             const char* a2 = last ? nA : cA + (size_t)(t + 2) * kstep; const char* b2 = last ? nB : cB + (size_t)(t + 2) * kstep;
;             const char* a3 = a2 + kstep; const char* b3 = b2 + kstep;
;     ...
;             PG8_WAIT_V(8); PG8_WAIT_L(0); PG8_BAR; PG8_MMA(0, 0, At, B0); PG8_MMA(0, 1, At, B1); PG8_BAR; PG8_SCHED;
;             PG8_LDA(At, 1, 1); PG8_STAGE(PG8_SB(1, 0), b3, voffB); PG8_STAGE(PG8_SB(1, 1), b3 + hstep, voffB); PG8_STAGE(PG8_SA(1, 0), a3, voffA);
;             PG8_WAIT_V(8); PG8_WAIT_L(0); PG8_BAR; PG8_MMA(1, 0, At, B0); PG8_MMA(1, 1, At, B1); PG8_BAR; PG8_SCHED;
;         }
	s_setprio 1
	s_waitcnt lgkmcnt(0)
	v_mfma_f32_16x16x32_bf16 v[126:129], v[136:139], v[198:201], v[126:129]
	v_mfma_f32_16x16x32_bf16 v[122:125], v[160:163], v[198:201], v[122:125]
	v_mfma_f32_16x16x32_bf16 v[110:113], v[136:139], v[206:209], v[110:113]
	v_mfma_f32_16x16x32_bf16 v[106:109], v[160:163], v[206:209], v[106:109]
	v_mfma_f32_16x16x32_bf16 v[94:97], v[136:139], v[214:217], v[94:97]
	v_mfma_f32_16x16x32_bf16 v[90:93], v[160:163], v[214:217], v[90:93]
	v_mfma_f32_16x16x32_bf16 v[78:81], v[136:139], v[222:225], v[78:81]
	v_mfma_f32_16x16x32_bf16 v[74:77], v[160:163], v[222:225], v[74:77]
	v_mfma_f32_16x16x32_bf16 v[126:129], v[156:159], v[202:205], v[126:129]
	v_mfma_f32_16x16x32_bf16 v[122:125], v[164:167], v[202:205], v[122:125]
	v_mfma_f32_16x16x32_bf16 v[110:113], v[156:159], v[210:213], v[110:113]
	v_mfma_f32_16x16x32_bf16 v[106:109], v[164:167], v[210:213], v[106:109]
	v_mfma_f32_16x16x32_bf16 v[94:97], v[156:159], v[218:221], v[94:97]
	v_mfma_f32_16x16x32_bf16 v[90:93], v[164:167], v[218:221], v[90:93]
	v_mfma_f32_16x16x32_bf16 v[78:81], v[156:159], v[226:229], v[78:81]
	v_mfma_f32_16x16x32_bf16 v[74:77], v[164:167], v[226:229], v[74:77]
	s_setprio 0
	s_setprio 1
	v_mfma_f32_16x16x32_bf16 v[118:121], v[168:171], v[198:201], v[118:121]
	v_mfma_f32_16x16x32_bf16 v[114:117], v[176:179], v[198:201], v[114:117]
	v_mfma_f32_16x16x32_bf16 v[102:105], v[168:171], v[206:209], v[102:105]
	v_mfma_f32_16x16x32_bf16 v[98:101], v[176:179], v[206:209], v[98:101]
	v_mfma_f32_16x16x32_bf16 v[86:89], v[168:171], v[214:217], v[86:89]
	v_mfma_f32_16x16x32_bf16 v[82:85], v[176:179], v[214:217], v[82:85]
	v_mfma_f32_16x16x32_bf16 v[70:73], v[168:171], v[222:225], v[70:73]
	v_mfma_f32_16x16x32_bf16 v[66:69], v[176:179], v[222:225], v[66:69]
	v_mfma_f32_16x16x32_bf16 v[118:121], v[172:175], v[202:205], v[118:121]
	v_mfma_f32_16x16x32_bf16 v[114:117], v[180:183], v[202:205], v[114:117]
	v_mfma_f32_16x16x32_bf16 v[102:105], v[172:175], v[210:213], v[102:105]
	v_mfma_f32_16x16x32_bf16 v[98:101], v[180:183], v[210:213], v[98:101]
	v_mfma_f32_16x16x32_bf16 v[86:89], v[172:175], v[218:221], v[86:89]
	v_mfma_f32_16x16x32_bf16 v[82:85], v[180:183], v[218:221], v[82:85]
	v_mfma_f32_16x16x32_bf16 v[70:73], v[172:175], v[226:229], v[70:73]
	v_mfma_f32_16x16x32_bf16 v[66:69], v[180:183], v[226:229], v[66:69]
	s_setprio 0
	s_barrier
	s_add_i32 s26, s30, s43
	v_lshl_add_u64 v[140:141], v[140:141], 0, s[34:35]
	s_mov_b32 m0, s26
	ds_read_b128 v[198:201], v145 offset:49152
	ds_read_b128 v[202:205], v145 offset:50176
	ds_read_b128 v[206:209], v145 offset:51200
	ds_read_b128 v[210:213], v145 offset:52224
	ds_read_b128 v[214:217], v145 offset:53248
	ds_read_b128 v[218:221], v145 offset:54272
	ds_read_b128 v[222:225], v145 offset:55296
	ds_read_b128 v[226:229], v145 offset:56320
	global_load_lds_dwordx4 v[140:141], off
	s_add_i32 m0, s26, 0x2000
	s_add_u32 s26, s54, 0xb0080
	v_lshl_add_u64 v[140:141], v[192:193], 0, s[34:35]
	s_addc_u32 s27, s55, 0
	s_add_i32 s30, s50, s43
	global_load_lds_dwordx4 v[140:141], off
	v_lshl_add_u64 v[140:141], s[26:27], 0, v[0:1]
	s_mov_b32 m0, s30
	s_nop 0
	global_load_lds_dwordx4 v[140:141], off
	v_lshl_add_u64 v[140:141], s[26:27], 0, v[130:131]
	s_add_i32 m0, s30, 0x2000
	s_nop 0
	global_load_lds_dwordx4 v[140:141], off
	v_lshl_add_u64 v[140:141], v[230:231], 0, s[34:35]
	s_mov_b32 m0, s60
	s_nop 0
	global_load_lds_dwordx4 v[140:141], off
	v_lshl_add_u64 v[140:141], v[232:233], 0, s[34:35]
	s_mov_b32 m0, s61
	s_nop 0
	global_load_lds_dwordx4 v[140:141], off
	s_waitcnt vmcnt(8)
	s_waitcnt lgkmcnt(0)
	s_barrier
	s_setprio 1
	s_waitcnt lgkmcnt(0)
	v_mfma_f32_16x16x32_bf16 v[62:65], v[136:139], v[198:201], v[62:65]
	v_mfma_f32_16x16x32_bf16 v[58:61], v[160:163], v[198:201], v[58:61]
	v_mfma_f32_16x16x32_bf16 v[46:49], v[136:139], v[206:209], v[46:49]
	v_mfma_f32_16x16x32_bf16 v[42:45], v[160:163], v[206:209], v[42:45]
	v_mfma_f32_16x16x32_bf16 v[30:33], v[136:139], v[214:217], v[30:33]
	v_mfma_f32_16x16x32_bf16 v[26:29], v[160:163], v[214:217], v[26:29]
	v_mfma_f32_16x16x32_bf16 v[14:17], v[136:139], v[222:225], v[14:17]
	v_mfma_f32_16x16x32_bf16 v[10:13], v[160:163], v[222:225], v[10:13]
	v_mfma_f32_16x16x32_bf16 v[62:65], v[156:159], v[202:205], v[62:65]
	v_mfma_f32_16x16x32_bf16 v[58:61], v[164:167], v[202:205], v[58:61]
	v_mfma_f32_16x16x32_bf16 v[46:49], v[156:159], v[210:213], v[46:49]
	v_mfma_f32_16x16x32_bf16 v[42:45], v[164:167], v[210:213], v[42:45]
	v_mfma_f32_16x16x32_bf16 v[30:33], v[156:159], v[218:221], v[30:33]
	v_mfma_f32_16x16x32_bf16 v[26:29], v[164:167], v[218:221], v[26:29]
	v_mfma_f32_16x16x32_bf16 v[14:17], v[156:159], v[226:229], v[14:17]
	v_mfma_f32_16x16x32_bf16 v[10:13], v[164:167], v[226:229], v[10:13]
	s_setprio 0
	s_setprio 1
	v_mfma_f32_16x16x32_bf16 v[54:57], v[168:171], v[198:201], v[54:57]
	v_mfma_f32_16x16x32_bf16 v[50:53], v[176:179], v[198:201], v[50:53]
	v_mfma_f32_16x16x32_bf16 v[38:41], v[168:171], v[206:209], v[38:41]
	v_mfma_f32_16x16x32_bf16 v[34:37], v[176:179], v[206:209], v[34:37]
	v_mfma_f32_16x16x32_bf16 v[22:25], v[168:171], v[214:217], v[22:25]
	v_mfma_f32_16x16x32_bf16 v[18:21], v[176:179], v[214:217], v[18:21]
	v_mfma_f32_16x16x32_bf16 v[6:9], v[168:171], v[222:225], v[6:9]
	v_mfma_f32_16x16x32_bf16 v[2:5], v[176:179], v[222:225], v[2:5]
	v_mfma_f32_16x16x32_bf16 v[54:57], v[172:175], v[202:205], v[54:57]
	v_mfma_f32_16x16x32_bf16 v[50:53], v[180:183], v[202:205], v[50:53]
	v_mfma_f32_16x16x32_bf16 v[38:41], v[172:175], v[210:213], v[38:41]
	v_mfma_f32_16x16x32_bf16 v[34:37], v[180:183], v[210:213], v[34:37]
	v_mfma_f32_16x16x32_bf16 v[22:25], v[172:175], v[218:221], v[22:25]
	v_mfma_f32_16x16x32_bf16 v[18:21], v[180:183], v[218:221], v[18:21]
	v_mfma_f32_16x16x32_bf16 v[6:9], v[172:175], v[226:229], v[6:9]
	v_mfma_f32_16x16x32_bf16 v[2:5], v[180:183], v[226:229], v[2:5]
	s_setprio 0
	s_add_i32 s71, s71, 2
	s_add_u32 s69, s69, 0x100
	s_addc_u32 s70, s70, 0
	s_mov_b64 s[50:51], s[52:53]
	s_add_u32 s52, s50, 0x100
	s_addc_u32 s53, s51, 0
	s_add_i32 s26, 0, 0x10000
	s_cmp_eq_u32 s71, 40
	s_cselect_b32 s57, s9, s53
	s_cselect_b32 s56, s8, s52
	s_cselect_b32 s55, s49, s70
	s_cselect_b32 s54, s48, s69
	s_add_i32 s30, 0, 0x14000
	s_cmp_gt_u32 s71, 41
	s_barrier
	s_cbranch_scc0 .LBB0_418
	s_and_b64 vcc, exec, s[22:23]
	s_cbranch_vccz .LBB0_421
	s_barrier
